# weight-conversion LN-fold loads batched instead of serialized; pipelined meta-row tail K-loop; tail units on earliest-finishing workgroups
# speedup vs baseline: 1.0391x; 1.0199x over previous
.LBB0_694:
	s_or_b64 exec, exec, s[16:17]
	v_lshlrev_b32_e32 v184, 2, v74
	global_load_dword v120, v184, s[8:9]
	global_load_dword v121, v184, s[10:11]
	v_lshlrev_b32_e32 v184, 2, v72
	global_load_dword v122, v184, s[8:9]
	global_load_dword v123, v184, s[10:11]
	v_lshlrev_b32_e32 v184, 2, v70
	global_load_dword v124, v184, s[8:9]
	global_load_dword v125, v184, s[10:11]
	v_lshlrev_b32_e32 v184, 2, v68
	global_load_dword v126, v184, s[8:9]
	global_load_dword v127, v184, s[10:11]
	v_lshlrev_b32_e32 v184, 2, v66
	global_load_dword v128, v184, s[8:9]
	global_load_dword v129, v184, s[10:11]
	v_lshlrev_b32_e32 v184, 2, v64
	global_load_dword v130, v184, s[8:9]
	global_load_dword v131, v184, s[10:11]
	v_lshlrev_b32_e32 v184, 2, v62
	global_load_dword v132, v184, s[8:9]
	global_load_dword v133, v184, s[10:11]
	v_lshlrev_b32_e32 v184, 2, v60
	global_load_dword v134, v184, s[8:9]
	global_load_dword v135, v184, s[10:11]
	v_lshlrev_b32_e32 v184, 2, v58
	global_load_dword v136, v184, s[8:9]
	global_load_dword v137, v184, s[10:11]
	v_lshlrev_b32_e32 v184, 2, v56
	global_load_dword v138, v184, s[8:9]
	global_load_dword v139, v184, s[10:11]
	v_lshlrev_b32_e32 v184, 2, v54
	global_load_dword v140, v184, s[8:9]
	global_load_dword v141, v184, s[10:11]
	v_lshlrev_b32_e32 v184, 2, v52
	global_load_dword v142, v184, s[8:9]
	global_load_dword v143, v184, s[10:11]
	v_lshlrev_b32_e32 v184, 2, v50
	global_load_dword v144, v184, s[8:9]
	global_load_dword v145, v184, s[10:11]
	v_lshlrev_b32_e32 v184, 2, v48
	global_load_dword v146, v184, s[8:9]
	global_load_dword v147, v184, s[10:11]
	v_lshlrev_b32_e32 v184, 2, v46
	global_load_dword v148, v184, s[8:9]
	global_load_dword v149, v184, s[10:11]
	v_lshlrev_b32_e32 v184, 2, v44
	global_load_dword v150, v184, s[8:9]
	global_load_dword v151, v184, s[10:11]
	v_lshlrev_b32_e32 v184, 2, v42
	global_load_dword v152, v184, s[8:9]
	global_load_dword v153, v184, s[10:11]
	v_lshlrev_b32_e32 v184, 2, v40
	global_load_dword v154, v184, s[8:9]
	global_load_dword v155, v184, s[10:11]
	v_lshlrev_b32_e32 v184, 2, v38
	global_load_dword v156, v184, s[8:9]
	global_load_dword v157, v184, s[10:11]
	v_lshlrev_b32_e32 v184, 2, v36
	global_load_dword v158, v184, s[8:9]
	global_load_dword v159, v184, s[10:11]
	v_lshlrev_b32_e32 v184, 2, v34
	global_load_dword v160, v184, s[8:9]
	global_load_dword v161, v184, s[10:11]
	v_lshlrev_b32_e32 v184, 2, v32
	global_load_dword v162, v184, s[8:9]
	global_load_dword v163, v184, s[10:11]
	v_lshlrev_b32_e32 v184, 2, v30
	global_load_dword v164, v184, s[8:9]
	global_load_dword v165, v184, s[10:11]
	v_lshlrev_b32_e32 v184, 2, v28
	global_load_dword v166, v184, s[8:9]
	global_load_dword v167, v184, s[10:11]
	v_lshlrev_b32_e32 v184, 2, v26
	global_load_dword v168, v184, s[8:9]
	global_load_dword v169, v184, s[10:11]
	v_lshlrev_b32_e32 v184, 2, v24
	global_load_dword v170, v184, s[8:9]
	global_load_dword v171, v184, s[10:11]
	v_lshlrev_b32_e32 v184, 2, v22
	global_load_dword v172, v184, s[8:9]
	global_load_dword v173, v184, s[10:11]
	v_lshlrev_b32_e32 v184, 2, v20
	global_load_dword v174, v184, s[8:9]
	global_load_dword v175, v184, s[10:11]
	v_lshlrev_b32_e32 v184, 2, v18
	global_load_dword v176, v184, s[8:9]
	global_load_dword v177, v184, s[10:11]
	v_lshlrev_b32_e32 v184, 2, v16
	global_load_dword v178, v184, s[8:9]
	global_load_dword v179, v184, s[10:11]
	v_lshlrev_b32_e32 v184, 2, v14
	global_load_dword v180, v184, s[8:9]
	global_load_dword v181, v184, s[10:11]
	v_lshlrev_b32_e32 v184, 2, v12
	global_load_dword v182, v184, s[8:9]
	global_load_dword v183, v184, s[10:11]
	s_waitcnt vmcnt(0)
	v_ashrrev_i32_e32 v75, 31, v74
	v_lshlrev_b64 v[76:77], 2, v[74:75]
	v_lshl_add_u64 v[74:75], s[10:11], 0, v[76:77]
	v_lshl_add_u64 v[76:77], s[8:9], 0, v[76:77]
	v_mov_b32_e32 v74, v121
	v_lshlrev_b64 v[12:13], 2, v[12:13]
	v_mov_b32_e32 v75, v120
	s_waitcnt vmcnt(0) lgkmcnt(0)
	v_fma_f32 v74, v73, v74, 0
	v_mul_f32_e32 v73, v73, v75
	v_bfe_u32 v75, v73, 16, 1
	v_add3_u32 v75, v73, v75, s34
	ds_write_b32 v3, v73
	v_ashrrev_i32_e32 v73, 31, v72
	v_lshlrev_b64 v[72:73], 2, v[72:73]
	v_lshl_add_u64 v[76:77], s[10:11], 0, v[72:73]
	v_lshl_add_u64 v[72:73], s[8:9], 0, v[72:73]
	v_mov_b32_e32 v76, v123
	v_and_b32_e32 v75, 0xffff0000, v75
	v_mov_b32_e32 v72, v122
	v_add_f32_e32 v75, 0, v75
	s_waitcnt vmcnt(0) lgkmcnt(0)
	v_fmac_f32_e32 v74, v71, v76
	v_mul_f32_e32 v71, v71, v72
	v_bfe_u32 v72, v71, 16, 1
	v_add3_u32 v72, v71, v72, s34
	ds_write_b32 v82, v71
	v_ashrrev_i32_e32 v71, 31, v70
	v_and_b32_e32 v72, 0xffff0000, v72
	v_lshlrev_b64 v[70:71], 2, v[70:71]
	v_add_f32_e32 v75, v75, v72
	v_lshl_add_u64 v[72:73], s[10:11], 0, v[70:71]
	v_lshl_add_u64 v[70:71], s[8:9], 0, v[70:71]
	v_mov_b32_e32 v72, v125
	s_waitcnt vmcnt(0) lgkmcnt(0)
	v_fmac_f32_e32 v74, v69, v72
	v_mov_b32_e32 v70, v124
	s_waitcnt vmcnt(0) lgkmcnt(0)
	v_mul_f32_e32 v69, v69, v70
	v_bfe_u32 v70, v69, 16, 1
	v_add3_u32 v70, v69, v70, s34
	ds_write_b32 v83, v69
	v_ashrrev_i32_e32 v69, 31, v68
	v_and_b32_e32 v70, 0xffff0000, v70
	v_lshlrev_b64 v[68:69], 2, v[68:69]
	v_add_f32_e32 v72, v75, v70
	v_lshl_add_u64 v[70:71], s[10:11], 0, v[68:69]
	v_lshl_add_u64 v[68:69], s[8:9], 0, v[68:69]
	v_mov_b32_e32 v70, v127
	s_waitcnt vmcnt(0) lgkmcnt(0)
	v_fmac_f32_e32 v74, v67, v70
	v_mov_b32_e32 v68, v126
	s_waitcnt vmcnt(0) lgkmcnt(0)
	v_mul_f32_e32 v67, v67, v68
	v_bfe_u32 v68, v67, 16, 1
	v_add3_u32 v68, v67, v68, s34
	ds_write_b32 v84, v67
	v_ashrrev_i32_e32 v67, 31, v66
	v_and_b32_e32 v68, 0xffff0000, v68
	v_lshlrev_b64 v[66:67], 2, v[66:67]
	v_add_f32_e32 v70, v72, v68
	v_lshl_add_u64 v[68:69], s[10:11], 0, v[66:67]
	v_lshl_add_u64 v[66:67], s[8:9], 0, v[66:67]
	v_mov_b32_e32 v68, v129
	s_waitcnt vmcnt(0) lgkmcnt(0)
	v_fmac_f32_e32 v74, v65, v68
	v_mov_b32_e32 v66, v128
	s_waitcnt vmcnt(0) lgkmcnt(0)
	v_mul_f32_e32 v65, v65, v66
	v_bfe_u32 v66, v65, 16, 1
	v_add3_u32 v66, v65, v66, s34
	ds_write_b32 v85, v65
	v_ashrrev_i32_e32 v65, 31, v64
	v_and_b32_e32 v66, 0xffff0000, v66
	v_lshlrev_b64 v[64:65], 2, v[64:65]
	v_add_f32_e32 v68, v70, v66
	v_lshl_add_u64 v[66:67], s[10:11], 0, v[64:65]
	v_lshl_add_u64 v[64:65], s[8:9], 0, v[64:65]
	v_mov_b32_e32 v66, v131
	s_waitcnt vmcnt(0) lgkmcnt(0)
	v_fmac_f32_e32 v74, v63, v66
	v_mov_b32_e32 v64, v130
	s_waitcnt vmcnt(0) lgkmcnt(0)
	v_mul_f32_e32 v63, v63, v64
	v_bfe_u32 v64, v63, 16, 1
	v_add3_u32 v64, v63, v64, s34
	ds_write_b32 v86, v63
	v_ashrrev_i32_e32 v63, 31, v62
	v_and_b32_e32 v64, 0xffff0000, v64
	v_lshlrev_b64 v[62:63], 2, v[62:63]
	v_add_f32_e32 v66, v68, v64
	v_lshl_add_u64 v[64:65], s[10:11], 0, v[62:63]
	v_lshl_add_u64 v[62:63], s[8:9], 0, v[62:63]
	v_mov_b32_e32 v64, v133
	s_waitcnt vmcnt(0) lgkmcnt(0)
	v_fmac_f32_e32 v74, v61, v64
	v_mov_b32_e32 v62, v132
	s_waitcnt vmcnt(0) lgkmcnt(0)
	v_mul_f32_e32 v61, v61, v62
	v_bfe_u32 v62, v61, 16, 1
	v_add3_u32 v62, v61, v62, s34
	ds_write_b32 v87, v61
	v_ashrrev_i32_e32 v61, 31, v60
	v_and_b32_e32 v62, 0xffff0000, v62
	v_lshlrev_b64 v[60:61], 2, v[60:61]
	v_add_f32_e32 v64, v66, v62
	v_lshl_add_u64 v[62:63], s[10:11], 0, v[60:61]
	v_lshl_add_u64 v[60:61], s[8:9], 0, v[60:61]
	v_mov_b32_e32 v62, v135
	s_waitcnt vmcnt(0) lgkmcnt(0)
	v_fmac_f32_e32 v74, v59, v62
	v_mov_b32_e32 v60, v134
	s_waitcnt vmcnt(0) lgkmcnt(0)
	v_mul_f32_e32 v59, v59, v60
	v_bfe_u32 v60, v59, 16, 1
	v_add3_u32 v60, v59, v60, s34
	ds_write_b32 v88, v59
	v_ashrrev_i32_e32 v59, 31, v58
	v_and_b32_e32 v60, 0xffff0000, v60
	v_lshlrev_b64 v[58:59], 2, v[58:59]
	v_add_f32_e32 v62, v64, v60
	v_lshl_add_u64 v[60:61], s[10:11], 0, v[58:59]
	v_lshl_add_u64 v[58:59], s[8:9], 0, v[58:59]
	v_mov_b32_e32 v60, v137
	s_waitcnt vmcnt(0) lgkmcnt(0)
	v_fmac_f32_e32 v74, v57, v60
	v_mov_b32_e32 v58, v136
	s_waitcnt vmcnt(0) lgkmcnt(0)
	v_mul_f32_e32 v57, v57, v58
	v_bfe_u32 v58, v57, 16, 1
	v_add3_u32 v58, v57, v58, s34
	ds_write_b32 v89, v57
	v_ashrrev_i32_e32 v57, 31, v56
	v_and_b32_e32 v58, 0xffff0000, v58
	v_lshlrev_b64 v[56:57], 2, v[56:57]
	v_add_f32_e32 v60, v62, v58
	v_lshl_add_u64 v[58:59], s[10:11], 0, v[56:57]
	v_lshl_add_u64 v[56:57], s[8:9], 0, v[56:57]
	v_mov_b32_e32 v58, v139
	s_waitcnt vmcnt(0) lgkmcnt(0)
	v_fmac_f32_e32 v74, v55, v58
	v_mov_b32_e32 v56, v138
	s_waitcnt vmcnt(0) lgkmcnt(0)
	v_mul_f32_e32 v55, v55, v56
	v_bfe_u32 v56, v55, 16, 1
	v_add3_u32 v56, v55, v56, s34
	ds_write_b32 v90, v55
	v_ashrrev_i32_e32 v55, 31, v54
	v_and_b32_e32 v56, 0xffff0000, v56
	v_lshlrev_b64 v[54:55], 2, v[54:55]
	v_add_f32_e32 v58, v60, v56
	v_lshl_add_u64 v[56:57], s[10:11], 0, v[54:55]
	v_lshl_add_u64 v[54:55], s[8:9], 0, v[54:55]
	v_mov_b32_e32 v56, v141
	s_waitcnt vmcnt(0) lgkmcnt(0)
	v_fmac_f32_e32 v74, v53, v56
	v_mov_b32_e32 v54, v140
	s_waitcnt vmcnt(0) lgkmcnt(0)
	v_mul_f32_e32 v53, v53, v54
	v_bfe_u32 v54, v53, 16, 1
	v_add3_u32 v54, v53, v54, s34
	ds_write_b32 v91, v53
	v_ashrrev_i32_e32 v53, 31, v52
	v_and_b32_e32 v54, 0xffff0000, v54
	v_lshlrev_b64 v[52:53], 2, v[52:53]
	v_add_f32_e32 v56, v58, v54
	v_lshl_add_u64 v[54:55], s[10:11], 0, v[52:53]
	v_lshl_add_u64 v[52:53], s[8:9], 0, v[52:53]
	v_mov_b32_e32 v54, v143
	s_waitcnt vmcnt(0) lgkmcnt(0)
	v_fmac_f32_e32 v74, v51, v54
	v_mov_b32_e32 v52, v142
	s_waitcnt vmcnt(0) lgkmcnt(0)
	v_mul_f32_e32 v51, v51, v52
	v_bfe_u32 v52, v51, 16, 1
	v_add3_u32 v52, v51, v52, s34
	ds_write_b32 v92, v51
	v_ashrrev_i32_e32 v51, 31, v50
	v_and_b32_e32 v52, 0xffff0000, v52
	v_lshlrev_b64 v[50:51], 2, v[50:51]
	v_add_f32_e32 v54, v56, v52
	v_lshl_add_u64 v[52:53], s[10:11], 0, v[50:51]
	v_lshl_add_u64 v[50:51], s[8:9], 0, v[50:51]
	v_mov_b32_e32 v52, v145
	s_waitcnt vmcnt(0) lgkmcnt(0)
	v_fmac_f32_e32 v74, v49, v52
	v_mov_b32_e32 v50, v144
	s_waitcnt vmcnt(0) lgkmcnt(0)
	v_mul_f32_e32 v49, v49, v50
	v_bfe_u32 v50, v49, 16, 1
	v_add3_u32 v50, v49, v50, s34
	ds_write_b32 v93, v49
	v_ashrrev_i32_e32 v49, 31, v48
	v_and_b32_e32 v50, 0xffff0000, v50
	v_lshlrev_b64 v[48:49], 2, v[48:49]
	v_add_f32_e32 v52, v54, v50
	v_lshl_add_u64 v[50:51], s[10:11], 0, v[48:49]
	v_lshl_add_u64 v[48:49], s[8:9], 0, v[48:49]
	v_mov_b32_e32 v50, v147
	s_waitcnt vmcnt(0) lgkmcnt(0)
	v_fmac_f32_e32 v74, v47, v50
	v_mov_b32_e32 v48, v146
	s_waitcnt vmcnt(0) lgkmcnt(0)
	v_mul_f32_e32 v47, v47, v48
	v_bfe_u32 v48, v47, 16, 1
	v_add3_u32 v48, v47, v48, s34
	ds_write_b32 v94, v47
	v_ashrrev_i32_e32 v47, 31, v46
	v_and_b32_e32 v48, 0xffff0000, v48
	v_lshlrev_b64 v[46:47], 2, v[46:47]
	v_add_f32_e32 v50, v52, v48
	v_lshl_add_u64 v[48:49], s[10:11], 0, v[46:47]
	v_lshl_add_u64 v[46:47], s[8:9], 0, v[46:47]
	v_mov_b32_e32 v48, v149
	s_waitcnt vmcnt(0) lgkmcnt(0)
	v_fmac_f32_e32 v74, v45, v48
	v_mov_b32_e32 v46, v148
	s_waitcnt vmcnt(0) lgkmcnt(0)
	v_mul_f32_e32 v45, v45, v46
	v_bfe_u32 v46, v45, 16, 1
	v_add3_u32 v46, v45, v46, s34
	ds_write_b32 v95, v45
	v_ashrrev_i32_e32 v45, 31, v44
	v_and_b32_e32 v46, 0xffff0000, v46
	v_lshlrev_b64 v[44:45], 2, v[44:45]
	v_add_f32_e32 v48, v50, v46
	v_lshl_add_u64 v[46:47], s[10:11], 0, v[44:45]
	v_lshl_add_u64 v[44:45], s[8:9], 0, v[44:45]
	v_mov_b32_e32 v46, v151
	s_waitcnt vmcnt(0) lgkmcnt(0)
	v_fmac_f32_e32 v74, v43, v46
	v_mov_b32_e32 v44, v150
	s_waitcnt vmcnt(0) lgkmcnt(0)
	v_mul_f32_e32 v43, v43, v44
	v_bfe_u32 v44, v43, 16, 1
	v_add3_u32 v44, v43, v44, s34
	ds_write_b32 v96, v43
	v_ashrrev_i32_e32 v43, 31, v42
	v_and_b32_e32 v44, 0xffff0000, v44
	v_lshlrev_b64 v[42:43], 2, v[42:43]
	v_add_f32_e32 v46, v48, v44
	v_lshl_add_u64 v[44:45], s[10:11], 0, v[42:43]
	v_lshl_add_u64 v[42:43], s[8:9], 0, v[42:43]
	v_mov_b32_e32 v44, v153
	s_waitcnt vmcnt(0) lgkmcnt(0)
	v_fmac_f32_e32 v74, v41, v44
	v_mov_b32_e32 v42, v152
	s_waitcnt vmcnt(0) lgkmcnt(0)
	v_mul_f32_e32 v41, v41, v42
	v_bfe_u32 v42, v41, 16, 1
	v_add3_u32 v42, v41, v42, s34
	ds_write_b32 v97, v41
	v_ashrrev_i32_e32 v41, 31, v40
	v_and_b32_e32 v42, 0xffff0000, v42
	v_lshlrev_b64 v[40:41], 2, v[40:41]
	v_add_f32_e32 v44, v46, v42
	v_lshl_add_u64 v[42:43], s[10:11], 0, v[40:41]
	v_lshl_add_u64 v[40:41], s[8:9], 0, v[40:41]
	v_mov_b32_e32 v42, v155
	s_waitcnt vmcnt(0) lgkmcnt(0)
	v_fmac_f32_e32 v74, v39, v42
	v_mov_b32_e32 v40, v154
	s_waitcnt vmcnt(0) lgkmcnt(0)
	v_mul_f32_e32 v39, v39, v40
	v_bfe_u32 v40, v39, 16, 1
	v_add3_u32 v40, v39, v40, s34
	ds_write_b32 v98, v39
	v_ashrrev_i32_e32 v39, 31, v38
	v_and_b32_e32 v40, 0xffff0000, v40
	v_lshlrev_b64 v[38:39], 2, v[38:39]
	v_add_f32_e32 v42, v44, v40
	v_lshl_add_u64 v[40:41], s[10:11], 0, v[38:39]
	v_lshl_add_u64 v[38:39], s[8:9], 0, v[38:39]
	v_mov_b32_e32 v40, v157
	s_waitcnt vmcnt(0) lgkmcnt(0)
	v_fmac_f32_e32 v74, v37, v40
	v_mov_b32_e32 v38, v156
	s_waitcnt vmcnt(0) lgkmcnt(0)
	v_mul_f32_e32 v37, v37, v38
	v_bfe_u32 v38, v37, 16, 1
	v_add3_u32 v38, v37, v38, s34
	ds_write_b32 v99, v37
	v_ashrrev_i32_e32 v37, 31, v36
	v_and_b32_e32 v38, 0xffff0000, v38
	v_lshlrev_b64 v[36:37], 2, v[36:37]
	v_add_f32_e32 v40, v42, v38
	v_lshl_add_u64 v[38:39], s[10:11], 0, v[36:37]
	v_lshl_add_u64 v[36:37], s[8:9], 0, v[36:37]
	v_mov_b32_e32 v38, v159
	s_waitcnt vmcnt(0) lgkmcnt(0)
	v_fmac_f32_e32 v74, v35, v38
	v_mov_b32_e32 v36, v158
	s_waitcnt vmcnt(0) lgkmcnt(0)
	v_mul_f32_e32 v35, v35, v36
	v_bfe_u32 v36, v35, 16, 1
	v_add3_u32 v36, v35, v36, s34
	ds_write_b32 v100, v35
	v_ashrrev_i32_e32 v35, 31, v34
	v_and_b32_e32 v36, 0xffff0000, v36
	v_lshlrev_b64 v[34:35], 2, v[34:35]
	v_add_f32_e32 v38, v40, v36
	v_lshl_add_u64 v[36:37], s[10:11], 0, v[34:35]
	v_lshl_add_u64 v[34:35], s[8:9], 0, v[34:35]
	v_mov_b32_e32 v36, v161
	s_waitcnt vmcnt(0) lgkmcnt(0)
	v_fmac_f32_e32 v74, v33, v36
	v_mov_b32_e32 v34, v160
	s_waitcnt vmcnt(0) lgkmcnt(0)
	v_mul_f32_e32 v33, v33, v34
	v_bfe_u32 v34, v33, 16, 1
	v_add3_u32 v34, v33, v34, s34
	ds_write_b32 v101, v33
	v_ashrrev_i32_e32 v33, 31, v32
	v_and_b32_e32 v34, 0xffff0000, v34
	v_lshlrev_b64 v[32:33], 2, v[32:33]
	v_add_f32_e32 v36, v38, v34
	v_lshl_add_u64 v[34:35], s[10:11], 0, v[32:33]
	v_lshl_add_u64 v[32:33], s[8:9], 0, v[32:33]
	v_mov_b32_e32 v34, v163
	s_waitcnt vmcnt(0) lgkmcnt(0)
	v_fmac_f32_e32 v74, v31, v34
	v_mov_b32_e32 v32, v162
	s_waitcnt vmcnt(0) lgkmcnt(0)
	v_mul_f32_e32 v31, v31, v32
	v_bfe_u32 v32, v31, 16, 1
	v_add3_u32 v32, v31, v32, s34
	ds_write_b32 v102, v31
	v_ashrrev_i32_e32 v31, 31, v30
	v_and_b32_e32 v32, 0xffff0000, v32
	v_lshlrev_b64 v[30:31], 2, v[30:31]
	v_add_f32_e32 v34, v36, v32
	v_lshl_add_u64 v[32:33], s[10:11], 0, v[30:31]
	v_lshl_add_u64 v[30:31], s[8:9], 0, v[30:31]
	v_mov_b32_e32 v32, v165
	s_waitcnt vmcnt(0) lgkmcnt(0)
	v_fmac_f32_e32 v74, v29, v32
	v_mov_b32_e32 v30, v164
	s_waitcnt vmcnt(0) lgkmcnt(0)
	v_mul_f32_e32 v29, v29, v30
	v_bfe_u32 v30, v29, 16, 1
	v_add3_u32 v30, v29, v30, s34
	ds_write_b32 v103, v29
	v_ashrrev_i32_e32 v29, 31, v28
	v_and_b32_e32 v30, 0xffff0000, v30
	v_lshlrev_b64 v[28:29], 2, v[28:29]
	v_add_f32_e32 v32, v34, v30
	v_lshl_add_u64 v[30:31], s[10:11], 0, v[28:29]
	v_lshl_add_u64 v[28:29], s[8:9], 0, v[28:29]
	v_mov_b32_e32 v30, v167
	s_waitcnt vmcnt(0) lgkmcnt(0)
	v_fmac_f32_e32 v74, v27, v30
	v_mov_b32_e32 v28, v166
	s_waitcnt vmcnt(0) lgkmcnt(0)
	v_mul_f32_e32 v27, v27, v28
	v_bfe_u32 v28, v27, 16, 1
	v_add3_u32 v28, v27, v28, s34
	ds_write_b32 v104, v27
	v_ashrrev_i32_e32 v27, 31, v26
	v_and_b32_e32 v28, 0xffff0000, v28
	v_lshlrev_b64 v[26:27], 2, v[26:27]
	v_add_f32_e32 v30, v32, v28
	v_lshl_add_u64 v[28:29], s[10:11], 0, v[26:27]
	v_lshl_add_u64 v[26:27], s[8:9], 0, v[26:27]
	v_mov_b32_e32 v28, v169
	s_waitcnt vmcnt(0) lgkmcnt(0)
	v_fmac_f32_e32 v74, v25, v28
	v_mov_b32_e32 v26, v168
	s_waitcnt vmcnt(0) lgkmcnt(0)
	v_mul_f32_e32 v25, v25, v26
	v_bfe_u32 v26, v25, 16, 1
	v_add3_u32 v26, v25, v26, s34
	ds_write_b32 v105, v25
	v_ashrrev_i32_e32 v25, 31, v24
	v_and_b32_e32 v26, 0xffff0000, v26
	v_lshlrev_b64 v[24:25], 2, v[24:25]
	v_add_f32_e32 v28, v30, v26
	v_lshl_add_u64 v[26:27], s[10:11], 0, v[24:25]
	v_lshl_add_u64 v[24:25], s[8:9], 0, v[24:25]
	v_mov_b32_e32 v26, v171
	s_waitcnt vmcnt(0) lgkmcnt(0)
	v_fmac_f32_e32 v74, v23, v26
	v_mov_b32_e32 v24, v170
	s_waitcnt vmcnt(0) lgkmcnt(0)
	v_mul_f32_e32 v23, v23, v24
	v_bfe_u32 v24, v23, 16, 1
	v_add3_u32 v24, v23, v24, s34
	ds_write_b32 v106, v23
	v_ashrrev_i32_e32 v23, 31, v22
	v_and_b32_e32 v24, 0xffff0000, v24
	v_lshlrev_b64 v[22:23], 2, v[22:23]
	v_add_f32_e32 v26, v28, v24
	v_lshl_add_u64 v[24:25], s[10:11], 0, v[22:23]
	v_lshl_add_u64 v[22:23], s[8:9], 0, v[22:23]
	v_mov_b32_e32 v24, v173
	s_waitcnt vmcnt(0) lgkmcnt(0)
	v_fmac_f32_e32 v74, v21, v24
	v_mov_b32_e32 v22, v172
	s_waitcnt vmcnt(0) lgkmcnt(0)
	v_mul_f32_e32 v21, v21, v22
	v_bfe_u32 v22, v21, 16, 1
	v_add3_u32 v22, v21, v22, s34
	ds_write_b32 v107, v21
	v_ashrrev_i32_e32 v21, 31, v20
	v_and_b32_e32 v22, 0xffff0000, v22
	v_lshlrev_b64 v[20:21], 2, v[20:21]
	v_add_f32_e32 v24, v26, v22
	v_lshl_add_u64 v[22:23], s[10:11], 0, v[20:21]
	v_lshl_add_u64 v[20:21], s[8:9], 0, v[20:21]
	v_mov_b32_e32 v22, v175
	s_waitcnt vmcnt(0) lgkmcnt(0)
	v_fmac_f32_e32 v74, v19, v22
	v_mov_b32_e32 v20, v174
	s_waitcnt vmcnt(0) lgkmcnt(0)
	v_mul_f32_e32 v19, v19, v20
	v_bfe_u32 v20, v19, 16, 1
	v_add3_u32 v20, v19, v20, s34
	ds_write_b32 v108, v19
	v_ashrrev_i32_e32 v19, 31, v18
	v_and_b32_e32 v20, 0xffff0000, v20
	v_lshlrev_b64 v[18:19], 2, v[18:19]
	v_add_f32_e32 v22, v24, v20
	v_lshl_add_u64 v[20:21], s[10:11], 0, v[18:19]
	v_lshl_add_u64 v[18:19], s[8:9], 0, v[18:19]
	v_mov_b32_e32 v20, v177
	s_waitcnt vmcnt(0) lgkmcnt(0)
	v_fmac_f32_e32 v74, v17, v20
	v_mov_b32_e32 v18, v176
	s_waitcnt vmcnt(0) lgkmcnt(0)
	v_mul_f32_e32 v17, v17, v18
	v_bfe_u32 v18, v17, 16, 1
	v_add3_u32 v18, v17, v18, s34
	ds_write_b32 v109, v17
	v_ashrrev_i32_e32 v17, 31, v16
	v_and_b32_e32 v18, 0xffff0000, v18
	v_lshlrev_b64 v[16:17], 2, v[16:17]
	v_add_f32_e32 v20, v22, v18
	v_lshl_add_u64 v[18:19], s[10:11], 0, v[16:17]
	v_lshl_add_u64 v[16:17], s[8:9], 0, v[16:17]
	v_mov_b32_e32 v18, v179
	s_waitcnt vmcnt(0) lgkmcnt(0)
	v_fmac_f32_e32 v74, v15, v18
	v_mov_b32_e32 v16, v178
	s_waitcnt vmcnt(0) lgkmcnt(0)
	v_mul_f32_e32 v15, v15, v16
	v_bfe_u32 v16, v15, 16, 1
	v_add3_u32 v16, v15, v16, s34
	ds_write_b32 v110, v15
	v_ashrrev_i32_e32 v15, 31, v14
	v_and_b32_e32 v16, 0xffff0000, v16
	v_lshlrev_b64 v[14:15], 2, v[14:15]
	v_add_f32_e32 v18, v20, v16
	v_lshl_add_u64 v[16:17], s[10:11], 0, v[14:15]
	v_lshl_add_u64 v[14:15], s[8:9], 0, v[14:15]
	v_mov_b32_e32 v14, v180
	s_waitcnt vmcnt(0) lgkmcnt(0)
	v_mul_f32_e32 v15, v116, v14
	v_mov_b32_e32 v16, v181
	ds_write_b32 v111, v15
	v_bfe_u32 v14, v15, 16, 1
	v_add3_u32 v14, v15, v14, s34
	v_and_b32_e32 v14, 0xffff0000, v14
	v_add_f32_e32 v14, v18, v14
	s_waitcnt vmcnt(0) lgkmcnt(0)
	v_fmac_f32_e32 v74, v116, v16
	v_lshl_add_u64 v[16:17], s[10:11], 0, v[12:13]
	v_lshl_add_u64 v[12:13], s[8:9], 0, v[12:13]
	v_mov_b32_e32 v12, v182
	s_waitcnt vmcnt(0) lgkmcnt(0)
	v_mul_f32_e32 v13, v115, v12
	v_mov_b32_e32 v15, v183
	v_bfe_u32 v12, v13, 16, 1
	v_add3_u32 v12, v13, v12, s34
	v_and_b32_e32 v12, 0xffff0000, v12
	v_add_f32_e32 v12, v14, v12
	ds_write_b32 v112, v13
	ds_bpermute_b32 v13, v113, v12
	s_waitcnt vmcnt(0) lgkmcnt(0)
	v_fmac_f32_e32 v74, v115, v15
	ds_bpermute_b32 v14, v113, v74
	s_and_saveexec_b64 s[16:17], s[0:1]
	s_cbranch_execz .LBB0_622
	v_add_f32_e32 v12, v12, v13
	v_mul_f32_e32 v12, 0x4f800000, v12
	s_waitcnt lgkmcnt(0)
	v_add_f32_e32 v16, v74, v14
	v_rndne_f32_e32 v14, v12
	s_mov_b32 s3, 0x2f800000
	v_mul_f32_e64 v12, |v14|, s3
	v_floor_f32_e32 v12, v12
	s_mov_b32 s15, 0xcf800000
	v_fma_f32 v13, v12, s15, |v14|
	v_cvt_u32_f32_e32 v17, v13
	v_cvt_u32_f32_e32 v15, v12
	v_ashrrev_i32_e32 v18, 31, v14
	s_ashr_i32 s13, s12, 31
	v_xor_b32_e32 v14, v17, v18
	s_lshl_b64 s[12:13], s[12:13], 3
	v_xor_b32_e32 v15, v15, v18
	v_sub_co_u32_e32 v14, vcc, v14, v18
	v_lshl_add_u64 v[12:13], v[6:7], 0, s[12:13]
	s_nop 0
	v_subb_co_u32_e32 v15, vcc, v15, v18, vcc
	flat_atomic_add_x2 v[12:13], v[14:15]
	v_mul_f32_e32 v12, 0x4f800000, v16
	v_rndne_f32_e32 v14, v12
	v_mul_f32_e64 v12, |v14|, s3
	v_floor_f32_e32 v12, v12
	v_fma_f32 v13, v12, s15, |v14|
	v_cvt_u32_f32_e32 v16, v13
	v_cvt_u32_f32_e32 v15, v12
	v_ashrrev_i32_e32 v17, 31, v14
	v_lshl_add_u64 v[12:13], v[8:9], 0, s[12:13]
	v_xor_b32_e32 v14, v16, v17
	v_xor_b32_e32 v15, v15, v17
	v_sub_co_u32_e32 v14, vcc, v14, v17
	s_nop 1
	v_subb_co_u32_e32 v15, vcc, v15, v17, vcc
	flat_atomic_add_x2 v[12:13], v[14:15]
	s_branch .LBB0_622

.LBB0_907:
	s_andn2_b64 vcc, exec, s[14:15]
	s_cbranch_vccnz .LBB0_927
	s_add_i32 s0, s55, 0xa8
	s_ashr_i32 s1, s0, 31
	s_lshr_b32 s1, s1, 24
	s_add_i32 s1, s0, s1
	s_and_b32 s1, s1, 0xffffff00
	s_sub_i32 s15, s0, s1
	s_cmp_gt_i32 s15, 15
	v_mbcnt_lo_u32_b32 v1, -1, 0
	v_mbcnt_hi_u32_b32 v1, -1, v1
	s_cbranch_scc1 .LBB0_927
	s_waitcnt lgkmcnt(0)
	v_readlane_b32 s16, v255, 11
	s_mov_b32 s17, 0
	s_cmp_eq_u32 s16, 2
	s_cselect_b32 s17, 88, s17
	s_cmp_eq_u32 s16, 9
	s_cselect_b32 s17, 176, s17
	s_cmp_eq_u32 s16, 11
	s_cselect_b32 s17, 264, s17
	s_cmp_eq_u32 s17, 0
	s_cbranch_scc1 .Ltail_skip
	s_cmp_lg_u32 s86, 0
	s_cbranch_scc1 .Ltail_bar
	v_mov_b32_e32 v2, 0x3d00
	s_mov_b32 s18, 0

.LBB0_913:
	s_cmpk_eq_u32 s14, 0x160
	s_cbranch_scc0 .Ltail_k1024
	global_load_dwordx4 v[2:5], v[100:101], off
	global_load_dwordx4 v[6:9], v[96:97], off
	global_load_dwordx4 v[10:13], v[98:99], off
	global_load_dwordx4 v[48:51], v[100:101], off offset:32
	global_load_dwordx4 v[52:55], v[96:97], off offset:32
	global_load_dwordx4 v[56:59], v[98:99], off offset:32
	global_load_dwordx4 v[60:63], v[100:101], off offset:64
	global_load_dwordx4 v[64:67], v[96:97], off offset:64
	global_load_dwordx4 v[68:71], v[98:99], off offset:64
	global_load_dwordx4 v[72:75], v[100:101], off offset:96
	global_load_dwordx4 v[76:79], v[96:97], off offset:96
	global_load_dwordx4 v[80:83], v[98:99], off offset:96
	global_load_dwordx4 v[106:109], v[100:101], off offset:128
	global_load_dwordx4 v[110:113], v[96:97], off offset:128
	global_load_dwordx4 v[114:117], v[98:99], off offset:128
	global_load_dwordx4 v[118:121], v[100:101], off offset:160
	global_load_dwordx4 v[122:125], v[96:97], off offset:160
	global_load_dwordx4 v[126:129], v[98:99], off offset:160
	global_load_dwordx4 v[130:133], v[100:101], off offset:192
	global_load_dwordx4 v[134:137], v[96:97], off offset:192
	global_load_dwordx4 v[138:141], v[98:99], off offset:192
	global_load_dwordx4 v[142:145], v[100:101], off offset:224
	global_load_dwordx4 v[146:149], v[96:97], off offset:224
	global_load_dwordx4 v[150:153], v[98:99], off offset:224
	global_load_dwordx4 v[154:157], v[100:101], off offset:256
	global_load_dwordx4 v[158:161], v[96:97], off offset:256
	global_load_dwordx4 v[164:167], v[98:99], off offset:256
	global_load_dwordx4 v[168:171], v[100:101], off offset:288
	global_load_dwordx4 v[172:175], v[96:97], off offset:288
	global_load_dwordx4 v[176:179], v[98:99], off offset:288
	s_waitcnt vmcnt(27)
	v_mfma_f32_32x32x16_bf16 v[16:31], v[2:5], v[6:9], v[16:31]
	v_mfma_f32_32x32x16_bf16 v[32:47], v[2:5], v[10:13], v[32:47]
	global_load_dwordx4 v[2:5], v[100:101], off offset:320
	global_load_dwordx4 v[6:9], v[96:97], off offset:320
	global_load_dwordx4 v[10:13], v[98:99], off offset:320
	s_waitcnt vmcnt(27)
	v_mfma_f32_32x32x16_bf16 v[16:31], v[48:51], v[52:55], v[16:31]
	v_mfma_f32_32x32x16_bf16 v[32:47], v[48:51], v[56:59], v[32:47]
	global_load_dwordx4 v[48:51], v[100:101], off offset:352
	global_load_dwordx4 v[52:55], v[96:97], off offset:352
	global_load_dwordx4 v[56:59], v[98:99], off offset:352
	s_waitcnt vmcnt(27)
	v_mfma_f32_32x32x16_bf16 v[16:31], v[60:63], v[64:67], v[16:31]
	v_mfma_f32_32x32x16_bf16 v[32:47], v[60:63], v[68:71], v[32:47]
	global_load_dwordx4 v[60:63], v[100:101], off offset:384
	global_load_dwordx4 v[64:67], v[96:97], off offset:384
	global_load_dwordx4 v[68:71], v[98:99], off offset:384
	s_waitcnt vmcnt(27)
	v_mfma_f32_32x32x16_bf16 v[16:31], v[72:75], v[76:79], v[16:31]
	v_mfma_f32_32x32x16_bf16 v[32:47], v[72:75], v[80:83], v[32:47]
	global_load_dwordx4 v[72:75], v[100:101], off offset:416
	global_load_dwordx4 v[76:79], v[96:97], off offset:416
	global_load_dwordx4 v[80:83], v[98:99], off offset:416
	s_waitcnt vmcnt(27)
	v_mfma_f32_32x32x16_bf16 v[16:31], v[106:109], v[110:113], v[16:31]
	v_mfma_f32_32x32x16_bf16 v[32:47], v[106:109], v[114:117], v[32:47]
	global_load_dwordx4 v[106:109], v[100:101], off offset:448
	global_load_dwordx4 v[110:113], v[96:97], off offset:448
	global_load_dwordx4 v[114:117], v[98:99], off offset:448
	s_waitcnt vmcnt(27)
	v_mfma_f32_32x32x16_bf16 v[16:31], v[118:121], v[122:125], v[16:31]
	v_mfma_f32_32x32x16_bf16 v[32:47], v[118:121], v[126:129], v[32:47]
	global_load_dwordx4 v[118:121], v[100:101], off offset:480
	global_load_dwordx4 v[122:125], v[96:97], off offset:480
	global_load_dwordx4 v[126:129], v[98:99], off offset:480
	s_waitcnt vmcnt(27)
	v_mfma_f32_32x32x16_bf16 v[16:31], v[130:133], v[134:137], v[16:31]
	v_mfma_f32_32x32x16_bf16 v[32:47], v[130:133], v[138:141], v[32:47]
	global_load_dwordx4 v[130:133], v[100:101], off offset:512
	global_load_dwordx4 v[134:137], v[96:97], off offset:512
	global_load_dwordx4 v[138:141], v[98:99], off offset:512
	s_waitcnt vmcnt(27)
	v_mfma_f32_32x32x16_bf16 v[16:31], v[142:145], v[146:149], v[16:31]
	v_mfma_f32_32x32x16_bf16 v[32:47], v[142:145], v[150:153], v[32:47]
	global_load_dwordx4 v[142:145], v[100:101], off offset:544
	global_load_dwordx4 v[146:149], v[96:97], off offset:544
	global_load_dwordx4 v[150:153], v[98:99], off offset:544
	s_waitcnt vmcnt(27)
	v_mfma_f32_32x32x16_bf16 v[16:31], v[154:157], v[158:161], v[16:31]
	v_mfma_f32_32x32x16_bf16 v[32:47], v[154:157], v[164:167], v[32:47]
	global_load_dwordx4 v[154:157], v[100:101], off offset:576
	global_load_dwordx4 v[158:161], v[96:97], off offset:576
	global_load_dwordx4 v[164:167], v[98:99], off offset:576
	s_waitcnt vmcnt(27)
	v_mfma_f32_32x32x16_bf16 v[16:31], v[168:171], v[172:175], v[16:31]
	v_mfma_f32_32x32x16_bf16 v[32:47], v[168:171], v[176:179], v[32:47]
	global_load_dwordx4 v[168:171], v[100:101], off offset:608
	global_load_dwordx4 v[172:175], v[96:97], off offset:608
	global_load_dwordx4 v[176:179], v[98:99], off offset:608
	s_waitcnt vmcnt(27)
	v_mfma_f32_32x32x16_bf16 v[16:31], v[2:5], v[6:9], v[16:31]
	v_mfma_f32_32x32x16_bf16 v[32:47], v[2:5], v[10:13], v[32:47]
	global_load_dwordx4 v[2:5], v[100:101], off offset:640
	global_load_dwordx4 v[6:9], v[96:97], off offset:640
	global_load_dwordx4 v[10:13], v[98:99], off offset:640
	s_waitcnt vmcnt(27)
	v_mfma_f32_32x32x16_bf16 v[16:31], v[48:51], v[52:55], v[16:31]
	v_mfma_f32_32x32x16_bf16 v[32:47], v[48:51], v[56:59], v[32:47]
	global_load_dwordx4 v[48:51], v[100:101], off offset:672
	global_load_dwordx4 v[52:55], v[96:97], off offset:672
	global_load_dwordx4 v[56:59], v[98:99], off offset:672
	s_waitcnt vmcnt(27)
	v_mfma_f32_32x32x16_bf16 v[16:31], v[60:63], v[64:67], v[16:31]
	v_mfma_f32_32x32x16_bf16 v[32:47], v[60:63], v[68:71], v[32:47]
	s_waitcnt vmcnt(24)
	v_mfma_f32_32x32x16_bf16 v[16:31], v[72:75], v[76:79], v[16:31]
	v_mfma_f32_32x32x16_bf16 v[32:47], v[72:75], v[80:83], v[32:47]
	s_waitcnt vmcnt(21)
	v_mfma_f32_32x32x16_bf16 v[16:31], v[106:109], v[110:113], v[16:31]
	v_mfma_f32_32x32x16_bf16 v[32:47], v[106:109], v[114:117], v[32:47]
	s_waitcnt vmcnt(18)
	v_mfma_f32_32x32x16_bf16 v[16:31], v[118:121], v[122:125], v[16:31]
	v_mfma_f32_32x32x16_bf16 v[32:47], v[118:121], v[126:129], v[32:47]
	s_waitcnt vmcnt(15)
	v_mfma_f32_32x32x16_bf16 v[16:31], v[130:133], v[134:137], v[16:31]
	v_mfma_f32_32x32x16_bf16 v[32:47], v[130:133], v[138:141], v[32:47]
	s_waitcnt vmcnt(12)
	v_mfma_f32_32x32x16_bf16 v[16:31], v[142:145], v[146:149], v[16:31]
	v_mfma_f32_32x32x16_bf16 v[32:47], v[142:145], v[150:153], v[32:47]
	s_waitcnt vmcnt(9)
	v_mfma_f32_32x32x16_bf16 v[16:31], v[154:157], v[158:161], v[16:31]
	v_mfma_f32_32x32x16_bf16 v[32:47], v[154:157], v[164:167], v[32:47]
	s_waitcnt vmcnt(6)
	v_mfma_f32_32x32x16_bf16 v[16:31], v[168:171], v[172:175], v[16:31]
	v_mfma_f32_32x32x16_bf16 v[32:47], v[168:171], v[176:179], v[32:47]
	s_waitcnt vmcnt(3)
	v_mfma_f32_32x32x16_bf16 v[16:31], v[2:5], v[6:9], v[16:31]
	v_mfma_f32_32x32x16_bf16 v[32:47], v[2:5], v[10:13], v[32:47]
	s_waitcnt vmcnt(0)
	v_mfma_f32_32x32x16_bf16 v[16:31], v[48:51], v[52:55], v[16:31]
	v_mfma_f32_32x32x16_bf16 v[32:47], v[48:51], v[56:59], v[32:47]
	s_nop 7
	s_nop 3
	s_branch .LBB0_925
.Ltail_k1024:
	global_load_dwordx4 v[2:5], v[100:101], off
	global_load_dwordx4 v[6:9], v[96:97], off
	global_load_dwordx4 v[10:13], v[98:99], off
	global_load_dwordx4 v[48:51], v[100:101], off offset:32
	global_load_dwordx4 v[52:55], v[96:97], off offset:32
	global_load_dwordx4 v[56:59], v[98:99], off offset:32
	global_load_dwordx4 v[60:63], v[100:101], off offset:64
	global_load_dwordx4 v[64:67], v[96:97], off offset:64
	global_load_dwordx4 v[68:71], v[98:99], off offset:64
	global_load_dwordx4 v[72:75], v[100:101], off offset:96
	global_load_dwordx4 v[76:79], v[96:97], off offset:96
	global_load_dwordx4 v[80:83], v[98:99], off offset:96
	global_load_dwordx4 v[106:109], v[100:101], off offset:128
	global_load_dwordx4 v[110:113], v[96:97], off offset:128
	global_load_dwordx4 v[114:117], v[98:99], off offset:128
	global_load_dwordx4 v[118:121], v[100:101], off offset:160
	global_load_dwordx4 v[122:125], v[96:97], off offset:160
	global_load_dwordx4 v[126:129], v[98:99], off offset:160
	global_load_dwordx4 v[130:133], v[100:101], off offset:192
	global_load_dwordx4 v[134:137], v[96:97], off offset:192
	global_load_dwordx4 v[138:141], v[98:99], off offset:192
	global_load_dwordx4 v[142:145], v[100:101], off offset:224
	global_load_dwordx4 v[146:149], v[96:97], off offset:224
	global_load_dwordx4 v[150:153], v[98:99], off offset:224
	s_waitcnt vmcnt(21)
	v_mfma_f32_32x32x16_bf16 v[16:31], v[2:5], v[6:9], v[16:31]
	v_mfma_f32_32x32x16_bf16 v[32:47], v[2:5], v[10:13], v[32:47]
	s_waitcnt vmcnt(18)
	v_mfma_f32_32x32x16_bf16 v[16:31], v[48:51], v[52:55], v[16:31]
	v_mfma_f32_32x32x16_bf16 v[32:47], v[48:51], v[56:59], v[32:47]
	s_waitcnt vmcnt(15)
	v_mfma_f32_32x32x16_bf16 v[16:31], v[60:63], v[64:67], v[16:31]
	v_mfma_f32_32x32x16_bf16 v[32:47], v[60:63], v[68:71], v[32:47]
	s_waitcnt vmcnt(12)
	v_mfma_f32_32x32x16_bf16 v[16:31], v[72:75], v[76:79], v[16:31]
	v_mfma_f32_32x32x16_bf16 v[32:47], v[72:75], v[80:83], v[32:47]
	s_waitcnt vmcnt(9)
	v_mfma_f32_32x32x16_bf16 v[16:31], v[106:109], v[110:113], v[16:31]
	v_mfma_f32_32x32x16_bf16 v[32:47], v[106:109], v[114:117], v[32:47]
	s_waitcnt vmcnt(6)
	v_mfma_f32_32x32x16_bf16 v[16:31], v[118:121], v[122:125], v[16:31]
	v_mfma_f32_32x32x16_bf16 v[32:47], v[118:121], v[126:129], v[32:47]
	s_waitcnt vmcnt(3)
	v_mfma_f32_32x32x16_bf16 v[16:31], v[130:133], v[134:137], v[16:31]
	v_mfma_f32_32x32x16_bf16 v[32:47], v[130:133], v[138:141], v[32:47]
	s_waitcnt vmcnt(0)
	v_mfma_f32_32x32x16_bf16 v[16:31], v[142:145], v[146:149], v[16:31]
	v_mfma_f32_32x32x16_bf16 v[32:47], v[142:145], v[150:153], v[32:47]
	s_nop 7
	s_nop 3
	s_branch .LBB0_925

.LBB0_1026:
	s_or_b64 exec, exec, s[0:1]
	v_lshlrev_b32_e32 v184, 2, v74
	global_load_dword v120, v184, s[6:7]
	global_load_dword v121, v184, s[8:9]
	v_lshlrev_b32_e32 v184, 2, v72
	global_load_dword v122, v184, s[6:7]
	global_load_dword v123, v184, s[8:9]
	v_lshlrev_b32_e32 v184, 2, v70
	global_load_dword v124, v184, s[6:7]
	global_load_dword v125, v184, s[8:9]
	v_lshlrev_b32_e32 v184, 2, v68
	global_load_dword v126, v184, s[6:7]
	global_load_dword v127, v184, s[8:9]
	v_lshlrev_b32_e32 v184, 2, v66
	global_load_dword v128, v184, s[6:7]
	global_load_dword v129, v184, s[8:9]
	v_lshlrev_b32_e32 v184, 2, v64
	global_load_dword v130, v184, s[6:7]
	global_load_dword v131, v184, s[8:9]
	v_lshlrev_b32_e32 v184, 2, v62
	global_load_dword v132, v184, s[6:7]
	global_load_dword v133, v184, s[8:9]
	v_lshlrev_b32_e32 v184, 2, v60
	global_load_dword v134, v184, s[6:7]
	global_load_dword v135, v184, s[8:9]
	v_lshlrev_b32_e32 v184, 2, v58
	global_load_dword v136, v184, s[6:7]
	global_load_dword v137, v184, s[8:9]
	v_lshlrev_b32_e32 v184, 2, v56
	global_load_dword v138, v184, s[6:7]
	global_load_dword v139, v184, s[8:9]
	v_lshlrev_b32_e32 v184, 2, v54
	global_load_dword v140, v184, s[6:7]
	global_load_dword v141, v184, s[8:9]
	v_lshlrev_b32_e32 v184, 2, v52
	global_load_dword v142, v184, s[6:7]
	global_load_dword v143, v184, s[8:9]
	v_lshlrev_b32_e32 v184, 2, v50
	global_load_dword v144, v184, s[6:7]
	global_load_dword v145, v184, s[8:9]
	v_lshlrev_b32_e32 v184, 2, v48
	global_load_dword v146, v184, s[6:7]
	global_load_dword v147, v184, s[8:9]
	v_lshlrev_b32_e32 v184, 2, v46
	global_load_dword v148, v184, s[6:7]
	global_load_dword v149, v184, s[8:9]
	v_lshlrev_b32_e32 v184, 2, v44
	global_load_dword v150, v184, s[6:7]
	global_load_dword v151, v184, s[8:9]
	v_lshlrev_b32_e32 v184, 2, v42
	global_load_dword v152, v184, s[6:7]
	global_load_dword v153, v184, s[8:9]
	v_lshlrev_b32_e32 v184, 2, v40
	global_load_dword v154, v184, s[6:7]
	global_load_dword v155, v184, s[8:9]
	v_lshlrev_b32_e32 v184, 2, v38
	global_load_dword v156, v184, s[6:7]
	global_load_dword v157, v184, s[8:9]
	v_lshlrev_b32_e32 v184, 2, v36
	global_load_dword v158, v184, s[6:7]
	global_load_dword v159, v184, s[8:9]
	v_lshlrev_b32_e32 v184, 2, v34
	global_load_dword v160, v184, s[6:7]
	global_load_dword v161, v184, s[8:9]
	v_lshlrev_b32_e32 v184, 2, v32
	global_load_dword v162, v184, s[6:7]
	global_load_dword v163, v184, s[8:9]
	v_lshlrev_b32_e32 v184, 2, v30
	global_load_dword v164, v184, s[6:7]
	global_load_dword v165, v184, s[8:9]
	v_lshlrev_b32_e32 v184, 2, v28
	global_load_dword v166, v184, s[6:7]
	global_load_dword v167, v184, s[8:9]
	v_lshlrev_b32_e32 v184, 2, v26
	global_load_dword v168, v184, s[6:7]
	global_load_dword v169, v184, s[8:9]
	v_lshlrev_b32_e32 v184, 2, v24
	global_load_dword v170, v184, s[6:7]
	global_load_dword v171, v184, s[8:9]
	v_lshlrev_b32_e32 v184, 2, v22
	global_load_dword v172, v184, s[6:7]
	global_load_dword v173, v184, s[8:9]
	v_lshlrev_b32_e32 v184, 2, v20
	global_load_dword v174, v184, s[6:7]
	global_load_dword v175, v184, s[8:9]
	v_lshlrev_b32_e32 v184, 2, v18
	global_load_dword v176, v184, s[6:7]
	global_load_dword v177, v184, s[8:9]
	v_lshlrev_b32_e32 v184, 2, v16
	global_load_dword v178, v184, s[6:7]
	global_load_dword v179, v184, s[8:9]
	v_lshlrev_b32_e32 v184, 2, v14
	global_load_dword v180, v184, s[6:7]
	global_load_dword v181, v184, s[8:9]
	v_lshlrev_b32_e32 v184, 2, v12
	global_load_dword v182, v184, s[6:7]
	global_load_dword v183, v184, s[8:9]
	s_waitcnt vmcnt(0)
	v_ashrrev_i32_e32 v75, 31, v74
	v_lshlrev_b64 v[76:77], 2, v[74:75]
	v_lshl_add_u64 v[74:75], s[8:9], 0, v[76:77]
	v_lshl_add_u64 v[76:77], s[6:7], 0, v[76:77]
	v_mov_b32_e32 v74, v121
	v_lshlrev_b64 v[12:13], 2, v[12:13]
	v_mov_b32_e32 v75, v120
	s_waitcnt vmcnt(0) lgkmcnt(0)
	v_fma_f32 v74, v73, v74, 0
	v_mul_f32_e32 v73, v73, v75
	v_bfe_u32 v75, v73, 16, 1
	v_add3_u32 v75, v73, v75, s34
	ds_write_b32 v78, v73
	v_ashrrev_i32_e32 v73, 31, v72
	v_lshlrev_b64 v[72:73], 2, v[72:73]
	v_lshl_add_u64 v[76:77], s[8:9], 0, v[72:73]
	v_lshl_add_u64 v[72:73], s[6:7], 0, v[72:73]
	v_mov_b32_e32 v76, v123
	v_and_b32_e32 v75, 0xffff0000, v75
	v_mov_b32_e32 v72, v122
	v_add_f32_e32 v75, 0, v75
	s_waitcnt vmcnt(0) lgkmcnt(0)
	v_fmac_f32_e32 v74, v71, v76
	v_mul_f32_e32 v71, v71, v72
	v_bfe_u32 v72, v71, 16, 1
	v_add3_u32 v72, v71, v72, s34
	ds_write_b32 v79, v71
	v_ashrrev_i32_e32 v71, 31, v70
	v_and_b32_e32 v72, 0xffff0000, v72
	v_lshlrev_b64 v[70:71], 2, v[70:71]
	v_add_f32_e32 v75, v75, v72
	v_lshl_add_u64 v[72:73], s[8:9], 0, v[70:71]
	v_lshl_add_u64 v[70:71], s[6:7], 0, v[70:71]
	v_mov_b32_e32 v72, v125
	s_waitcnt vmcnt(0) lgkmcnt(0)
	v_fmac_f32_e32 v74, v69, v72
	v_mov_b32_e32 v70, v124
	s_waitcnt vmcnt(0) lgkmcnt(0)
	v_mul_f32_e32 v69, v69, v70
	v_bfe_u32 v70, v69, 16, 1
	v_add3_u32 v70, v69, v70, s34
	ds_write_b32 v80, v69
	v_ashrrev_i32_e32 v69, 31, v68
	v_and_b32_e32 v70, 0xffff0000, v70
	v_lshlrev_b64 v[68:69], 2, v[68:69]
	v_add_f32_e32 v72, v75, v70
	v_lshl_add_u64 v[70:71], s[8:9], 0, v[68:69]
	v_lshl_add_u64 v[68:69], s[6:7], 0, v[68:69]
	v_mov_b32_e32 v70, v127
	s_waitcnt vmcnt(0) lgkmcnt(0)
	v_fmac_f32_e32 v74, v67, v70
	v_mov_b32_e32 v68, v126
	s_waitcnt vmcnt(0) lgkmcnt(0)
	v_mul_f32_e32 v67, v67, v68
	v_bfe_u32 v68, v67, 16, 1
	v_add3_u32 v68, v67, v68, s34
	ds_write_b32 v81, v67
	v_ashrrev_i32_e32 v67, 31, v66
	v_and_b32_e32 v68, 0xffff0000, v68
	v_lshlrev_b64 v[66:67], 2, v[66:67]
	v_add_f32_e32 v70, v72, v68
	v_lshl_add_u64 v[68:69], s[8:9], 0, v[66:67]
	v_lshl_add_u64 v[66:67], s[6:7], 0, v[66:67]
	v_mov_b32_e32 v68, v129
	s_waitcnt vmcnt(0) lgkmcnt(0)
	v_fmac_f32_e32 v74, v65, v68
	v_mov_b32_e32 v66, v128
	s_waitcnt vmcnt(0) lgkmcnt(0)
	v_mul_f32_e32 v65, v65, v66
	v_bfe_u32 v66, v65, 16, 1
	v_add3_u32 v66, v65, v66, s34
	ds_write_b32 v82, v65
	v_ashrrev_i32_e32 v65, 31, v64
	v_and_b32_e32 v66, 0xffff0000, v66
	v_lshlrev_b64 v[64:65], 2, v[64:65]
	v_add_f32_e32 v68, v70, v66
	v_lshl_add_u64 v[66:67], s[8:9], 0, v[64:65]
	v_lshl_add_u64 v[64:65], s[6:7], 0, v[64:65]
	v_mov_b32_e32 v66, v131
	s_waitcnt vmcnt(0) lgkmcnt(0)
	v_fmac_f32_e32 v74, v63, v66
	v_mov_b32_e32 v64, v130
	s_waitcnt vmcnt(0) lgkmcnt(0)
	v_mul_f32_e32 v63, v63, v64
	v_bfe_u32 v64, v63, 16, 1
	v_add3_u32 v64, v63, v64, s34
	ds_write_b32 v83, v63
	v_ashrrev_i32_e32 v63, 31, v62
	v_and_b32_e32 v64, 0xffff0000, v64
	v_lshlrev_b64 v[62:63], 2, v[62:63]
	v_add_f32_e32 v66, v68, v64
	v_lshl_add_u64 v[64:65], s[8:9], 0, v[62:63]
	v_lshl_add_u64 v[62:63], s[6:7], 0, v[62:63]
	v_mov_b32_e32 v64, v133
	s_waitcnt vmcnt(0) lgkmcnt(0)
	v_fmac_f32_e32 v74, v61, v64
	v_mov_b32_e32 v62, v132
	s_waitcnt vmcnt(0) lgkmcnt(0)
	v_mul_f32_e32 v61, v61, v62
	v_bfe_u32 v62, v61, 16, 1
	v_add3_u32 v62, v61, v62, s34
	ds_write_b32 v84, v61
	v_ashrrev_i32_e32 v61, 31, v60
	v_and_b32_e32 v62, 0xffff0000, v62
	v_lshlrev_b64 v[60:61], 2, v[60:61]
	v_add_f32_e32 v64, v66, v62
	v_lshl_add_u64 v[62:63], s[8:9], 0, v[60:61]
	v_lshl_add_u64 v[60:61], s[6:7], 0, v[60:61]
	v_mov_b32_e32 v62, v135
	s_waitcnt vmcnt(0) lgkmcnt(0)
	v_fmac_f32_e32 v74, v59, v62
	v_mov_b32_e32 v60, v134
	s_waitcnt vmcnt(0) lgkmcnt(0)
	v_mul_f32_e32 v59, v59, v60
	v_bfe_u32 v60, v59, 16, 1
	v_add3_u32 v60, v59, v60, s34
	ds_write_b32 v85, v59
	v_ashrrev_i32_e32 v59, 31, v58
	v_and_b32_e32 v60, 0xffff0000, v60
	v_lshlrev_b64 v[58:59], 2, v[58:59]
	v_add_f32_e32 v62, v64, v60
	v_lshl_add_u64 v[60:61], s[8:9], 0, v[58:59]
	v_lshl_add_u64 v[58:59], s[6:7], 0, v[58:59]
	v_mov_b32_e32 v60, v137
	s_waitcnt vmcnt(0) lgkmcnt(0)
	v_fmac_f32_e32 v74, v57, v60
	v_mov_b32_e32 v58, v136
	s_waitcnt vmcnt(0) lgkmcnt(0)
	v_mul_f32_e32 v57, v57, v58
	v_bfe_u32 v58, v57, 16, 1
	v_add3_u32 v58, v57, v58, s34
	ds_write_b32 v86, v57
	v_ashrrev_i32_e32 v57, 31, v56
	v_and_b32_e32 v58, 0xffff0000, v58
	v_lshlrev_b64 v[56:57], 2, v[56:57]
	v_add_f32_e32 v60, v62, v58
	v_lshl_add_u64 v[58:59], s[8:9], 0, v[56:57]
	v_lshl_add_u64 v[56:57], s[6:7], 0, v[56:57]
	v_mov_b32_e32 v58, v139
	s_waitcnt vmcnt(0) lgkmcnt(0)
	v_fmac_f32_e32 v74, v55, v58
	v_mov_b32_e32 v56, v138
	s_waitcnt vmcnt(0) lgkmcnt(0)
	v_mul_f32_e32 v55, v55, v56
	v_bfe_u32 v56, v55, 16, 1
	v_add3_u32 v56, v55, v56, s34
	ds_write_b32 v87, v55
	v_ashrrev_i32_e32 v55, 31, v54
	v_and_b32_e32 v56, 0xffff0000, v56
	v_lshlrev_b64 v[54:55], 2, v[54:55]
	v_add_f32_e32 v58, v60, v56
	v_lshl_add_u64 v[56:57], s[8:9], 0, v[54:55]
	v_lshl_add_u64 v[54:55], s[6:7], 0, v[54:55]
	v_mov_b32_e32 v56, v141
	s_waitcnt vmcnt(0) lgkmcnt(0)
	v_fmac_f32_e32 v74, v53, v56
	v_mov_b32_e32 v54, v140
	s_waitcnt vmcnt(0) lgkmcnt(0)
	v_mul_f32_e32 v53, v53, v54
	v_bfe_u32 v54, v53, 16, 1
	v_add3_u32 v54, v53, v54, s34
	ds_write_b32 v88, v53
	v_ashrrev_i32_e32 v53, 31, v52
	v_and_b32_e32 v54, 0xffff0000, v54
	v_lshlrev_b64 v[52:53], 2, v[52:53]
	v_add_f32_e32 v56, v58, v54
	v_lshl_add_u64 v[54:55], s[8:9], 0, v[52:53]
	v_lshl_add_u64 v[52:53], s[6:7], 0, v[52:53]
	v_mov_b32_e32 v54, v143
	s_waitcnt vmcnt(0) lgkmcnt(0)
	v_fmac_f32_e32 v74, v51, v54
	v_mov_b32_e32 v52, v142
	s_waitcnt vmcnt(0) lgkmcnt(0)
	v_mul_f32_e32 v51, v51, v52
	v_bfe_u32 v52, v51, 16, 1
	v_add3_u32 v52, v51, v52, s34
	ds_write_b32 v89, v51
	v_ashrrev_i32_e32 v51, 31, v50
	v_and_b32_e32 v52, 0xffff0000, v52
	v_lshlrev_b64 v[50:51], 2, v[50:51]
	v_add_f32_e32 v54, v56, v52
	v_lshl_add_u64 v[52:53], s[8:9], 0, v[50:51]
	v_lshl_add_u64 v[50:51], s[6:7], 0, v[50:51]
	v_mov_b32_e32 v52, v145
	s_waitcnt vmcnt(0) lgkmcnt(0)
	v_fmac_f32_e32 v74, v49, v52
	v_mov_b32_e32 v50, v144
	s_waitcnt vmcnt(0) lgkmcnt(0)
	v_mul_f32_e32 v49, v49, v50
	v_bfe_u32 v50, v49, 16, 1
	v_add3_u32 v50, v49, v50, s34
	ds_write_b32 v90, v49
	v_ashrrev_i32_e32 v49, 31, v48
	v_and_b32_e32 v50, 0xffff0000, v50
	v_lshlrev_b64 v[48:49], 2, v[48:49]
	v_add_f32_e32 v52, v54, v50
	v_lshl_add_u64 v[50:51], s[8:9], 0, v[48:49]
	v_lshl_add_u64 v[48:49], s[6:7], 0, v[48:49]
	v_mov_b32_e32 v50, v147
	s_waitcnt vmcnt(0) lgkmcnt(0)
	v_fmac_f32_e32 v74, v47, v50
	v_mov_b32_e32 v48, v146
	s_waitcnt vmcnt(0) lgkmcnt(0)
	v_mul_f32_e32 v47, v47, v48
	v_bfe_u32 v48, v47, 16, 1
	v_add3_u32 v48, v47, v48, s34
	ds_write_b32 v91, v47
	v_ashrrev_i32_e32 v47, 31, v46
	v_and_b32_e32 v48, 0xffff0000, v48
	v_lshlrev_b64 v[46:47], 2, v[46:47]
	v_add_f32_e32 v50, v52, v48
	v_lshl_add_u64 v[48:49], s[8:9], 0, v[46:47]
	v_lshl_add_u64 v[46:47], s[6:7], 0, v[46:47]
	v_mov_b32_e32 v48, v149
	s_waitcnt vmcnt(0) lgkmcnt(0)
	v_fmac_f32_e32 v74, v45, v48
	v_mov_b32_e32 v46, v148
	s_waitcnt vmcnt(0) lgkmcnt(0)
	v_mul_f32_e32 v45, v45, v46
	v_bfe_u32 v46, v45, 16, 1
	v_add3_u32 v46, v45, v46, s34
	ds_write_b32 v92, v45
	v_ashrrev_i32_e32 v45, 31, v44
	v_and_b32_e32 v46, 0xffff0000, v46
	v_lshlrev_b64 v[44:45], 2, v[44:45]
	v_add_f32_e32 v48, v50, v46
	v_lshl_add_u64 v[46:47], s[8:9], 0, v[44:45]
	v_lshl_add_u64 v[44:45], s[6:7], 0, v[44:45]
	v_mov_b32_e32 v46, v151
	s_waitcnt vmcnt(0) lgkmcnt(0)
	v_fmac_f32_e32 v74, v43, v46
	v_mov_b32_e32 v44, v150
	s_waitcnt vmcnt(0) lgkmcnt(0)
	v_mul_f32_e32 v43, v43, v44
	v_bfe_u32 v44, v43, 16, 1
	v_add3_u32 v44, v43, v44, s34
	ds_write_b32 v93, v43
	v_ashrrev_i32_e32 v43, 31, v42
	v_and_b32_e32 v44, 0xffff0000, v44
	v_lshlrev_b64 v[42:43], 2, v[42:43]
	v_add_f32_e32 v46, v48, v44
	v_lshl_add_u64 v[44:45], s[8:9], 0, v[42:43]
	v_lshl_add_u64 v[42:43], s[6:7], 0, v[42:43]
	v_mov_b32_e32 v44, v153
	s_waitcnt vmcnt(0) lgkmcnt(0)
	v_fmac_f32_e32 v74, v41, v44
	v_mov_b32_e32 v42, v152
	s_waitcnt vmcnt(0) lgkmcnt(0)
	v_mul_f32_e32 v41, v41, v42
	v_bfe_u32 v42, v41, 16, 1
	v_add3_u32 v42, v41, v42, s34
	ds_write_b32 v94, v41
	v_ashrrev_i32_e32 v41, 31, v40
	v_and_b32_e32 v42, 0xffff0000, v42
	v_lshlrev_b64 v[40:41], 2, v[40:41]
	v_add_f32_e32 v44, v46, v42
	v_lshl_add_u64 v[42:43], s[8:9], 0, v[40:41]
	v_lshl_add_u64 v[40:41], s[6:7], 0, v[40:41]
	v_mov_b32_e32 v42, v155
	s_waitcnt vmcnt(0) lgkmcnt(0)
	v_fmac_f32_e32 v74, v39, v42
	v_mov_b32_e32 v40, v154
	s_waitcnt vmcnt(0) lgkmcnt(0)
	v_mul_f32_e32 v39, v39, v40
	v_bfe_u32 v40, v39, 16, 1
	v_add3_u32 v40, v39, v40, s34
	ds_write_b32 v95, v39
	v_ashrrev_i32_e32 v39, 31, v38
	v_and_b32_e32 v40, 0xffff0000, v40
	v_lshlrev_b64 v[38:39], 2, v[38:39]
	v_add_f32_e32 v42, v44, v40
	v_lshl_add_u64 v[40:41], s[8:9], 0, v[38:39]
	v_lshl_add_u64 v[38:39], s[6:7], 0, v[38:39]
	v_mov_b32_e32 v40, v157
	s_waitcnt vmcnt(0) lgkmcnt(0)
	v_fmac_f32_e32 v74, v37, v40
	v_mov_b32_e32 v38, v156
	s_waitcnt vmcnt(0) lgkmcnt(0)
	v_mul_f32_e32 v37, v37, v38
	v_bfe_u32 v38, v37, 16, 1
	v_add3_u32 v38, v37, v38, s34
	ds_write_b32 v96, v37
	v_ashrrev_i32_e32 v37, 31, v36
	v_and_b32_e32 v38, 0xffff0000, v38
	v_lshlrev_b64 v[36:37], 2, v[36:37]
	v_add_f32_e32 v40, v42, v38
	v_lshl_add_u64 v[38:39], s[8:9], 0, v[36:37]
	v_lshl_add_u64 v[36:37], s[6:7], 0, v[36:37]
	v_mov_b32_e32 v38, v159
	s_waitcnt vmcnt(0) lgkmcnt(0)
	v_fmac_f32_e32 v74, v35, v38
	v_mov_b32_e32 v36, v158
	s_waitcnt vmcnt(0) lgkmcnt(0)
	v_mul_f32_e32 v35, v35, v36
	v_bfe_u32 v36, v35, 16, 1
	v_add3_u32 v36, v35, v36, s34
	ds_write_b32 v97, v35
	v_ashrrev_i32_e32 v35, 31, v34
	v_and_b32_e32 v36, 0xffff0000, v36
	v_lshlrev_b64 v[34:35], 2, v[34:35]
	v_add_f32_e32 v38, v40, v36
	v_lshl_add_u64 v[36:37], s[8:9], 0, v[34:35]
	v_lshl_add_u64 v[34:35], s[6:7], 0, v[34:35]
	v_mov_b32_e32 v36, v161
	s_waitcnt vmcnt(0) lgkmcnt(0)
	v_fmac_f32_e32 v74, v33, v36
	v_mov_b32_e32 v34, v160
	s_waitcnt vmcnt(0) lgkmcnt(0)
	v_mul_f32_e32 v33, v33, v34
	v_bfe_u32 v34, v33, 16, 1
	v_add3_u32 v34, v33, v34, s34
	ds_write_b32 v98, v33
	v_ashrrev_i32_e32 v33, 31, v32
	v_and_b32_e32 v34, 0xffff0000, v34
	v_lshlrev_b64 v[32:33], 2, v[32:33]
	v_add_f32_e32 v36, v38, v34
	v_lshl_add_u64 v[34:35], s[8:9], 0, v[32:33]
	v_lshl_add_u64 v[32:33], s[6:7], 0, v[32:33]
	v_mov_b32_e32 v34, v163
	s_waitcnt vmcnt(0) lgkmcnt(0)
	v_fmac_f32_e32 v74, v31, v34
	v_mov_b32_e32 v32, v162
	s_waitcnt vmcnt(0) lgkmcnt(0)
	v_mul_f32_e32 v31, v31, v32
	v_bfe_u32 v32, v31, 16, 1
	v_add3_u32 v32, v31, v32, s34
	ds_write_b32 v99, v31
	v_ashrrev_i32_e32 v31, 31, v30
	v_and_b32_e32 v32, 0xffff0000, v32
	v_lshlrev_b64 v[30:31], 2, v[30:31]
	v_add_f32_e32 v34, v36, v32
	v_lshl_add_u64 v[32:33], s[8:9], 0, v[30:31]
	v_lshl_add_u64 v[30:31], s[6:7], 0, v[30:31]
	v_mov_b32_e32 v32, v165
	s_waitcnt vmcnt(0) lgkmcnt(0)
	v_fmac_f32_e32 v74, v29, v32
	v_mov_b32_e32 v30, v164
	s_waitcnt vmcnt(0) lgkmcnt(0)
	v_mul_f32_e32 v29, v29, v30
	v_bfe_u32 v30, v29, 16, 1
	v_add3_u32 v30, v29, v30, s34
	ds_write_b32 v100, v29
	v_ashrrev_i32_e32 v29, 31, v28
	v_and_b32_e32 v30, 0xffff0000, v30
	v_lshlrev_b64 v[28:29], 2, v[28:29]
	v_add_f32_e32 v32, v34, v30
	v_lshl_add_u64 v[30:31], s[8:9], 0, v[28:29]
	v_lshl_add_u64 v[28:29], s[6:7], 0, v[28:29]
	v_mov_b32_e32 v30, v167
	s_waitcnt vmcnt(0) lgkmcnt(0)
	v_fmac_f32_e32 v74, v27, v30
	v_mov_b32_e32 v28, v166
	s_waitcnt vmcnt(0) lgkmcnt(0)
	v_mul_f32_e32 v27, v27, v28
	v_bfe_u32 v28, v27, 16, 1
	v_add3_u32 v28, v27, v28, s34
	ds_write_b32 v101, v27
	v_ashrrev_i32_e32 v27, 31, v26
	v_and_b32_e32 v28, 0xffff0000, v28
	v_lshlrev_b64 v[26:27], 2, v[26:27]
	v_add_f32_e32 v30, v32, v28
	v_lshl_add_u64 v[28:29], s[8:9], 0, v[26:27]
	v_lshl_add_u64 v[26:27], s[6:7], 0, v[26:27]
	v_mov_b32_e32 v28, v169
	s_waitcnt vmcnt(0) lgkmcnt(0)
	v_fmac_f32_e32 v74, v25, v28
	v_mov_b32_e32 v26, v168
	s_waitcnt vmcnt(0) lgkmcnt(0)
	v_mul_f32_e32 v25, v25, v26
	v_bfe_u32 v26, v25, 16, 1
	v_add3_u32 v26, v25, v26, s34
	ds_write_b32 v102, v25
	v_ashrrev_i32_e32 v25, 31, v24
	v_and_b32_e32 v26, 0xffff0000, v26
	v_lshlrev_b64 v[24:25], 2, v[24:25]
	v_add_f32_e32 v28, v30, v26
	v_lshl_add_u64 v[26:27], s[8:9], 0, v[24:25]
	v_lshl_add_u64 v[24:25], s[6:7], 0, v[24:25]
	v_mov_b32_e32 v26, v171
	s_waitcnt vmcnt(0) lgkmcnt(0)
	v_fmac_f32_e32 v74, v23, v26
	v_mov_b32_e32 v24, v170
	s_waitcnt vmcnt(0) lgkmcnt(0)
	v_mul_f32_e32 v23, v23, v24
	v_bfe_u32 v24, v23, 16, 1
	v_add3_u32 v24, v23, v24, s34
	ds_write_b32 v103, v23
	v_ashrrev_i32_e32 v23, 31, v22
	v_and_b32_e32 v24, 0xffff0000, v24
	v_lshlrev_b64 v[22:23], 2, v[22:23]
	v_add_f32_e32 v26, v28, v24
	v_lshl_add_u64 v[24:25], s[8:9], 0, v[22:23]
	v_lshl_add_u64 v[22:23], s[6:7], 0, v[22:23]
	v_mov_b32_e32 v24, v173
	s_waitcnt vmcnt(0) lgkmcnt(0)
	v_fmac_f32_e32 v74, v21, v24
	v_mov_b32_e32 v22, v172
	s_waitcnt vmcnt(0) lgkmcnt(0)
	v_mul_f32_e32 v21, v21, v22
	v_bfe_u32 v22, v21, 16, 1
	v_add3_u32 v22, v21, v22, s34
	ds_write_b32 v104, v21
	v_ashrrev_i32_e32 v21, 31, v20
	v_and_b32_e32 v22, 0xffff0000, v22
	v_lshlrev_b64 v[20:21], 2, v[20:21]
	v_add_f32_e32 v24, v26, v22
	v_lshl_add_u64 v[22:23], s[8:9], 0, v[20:21]
	v_lshl_add_u64 v[20:21], s[6:7], 0, v[20:21]
	v_mov_b32_e32 v22, v175
	s_waitcnt vmcnt(0) lgkmcnt(0)
	v_fmac_f32_e32 v74, v19, v22
	v_mov_b32_e32 v20, v174
	s_waitcnt vmcnt(0) lgkmcnt(0)
	v_mul_f32_e32 v19, v19, v20
	v_bfe_u32 v20, v19, 16, 1
	v_add3_u32 v20, v19, v20, s34
	ds_write_b32 v105, v19
	v_ashrrev_i32_e32 v19, 31, v18
	v_and_b32_e32 v20, 0xffff0000, v20
	v_lshlrev_b64 v[18:19], 2, v[18:19]
	v_add_f32_e32 v22, v24, v20
	v_lshl_add_u64 v[20:21], s[8:9], 0, v[18:19]
	v_lshl_add_u64 v[18:19], s[6:7], 0, v[18:19]
	v_mov_b32_e32 v20, v177
	s_waitcnt vmcnt(0) lgkmcnt(0)
	v_fmac_f32_e32 v74, v17, v20
	v_mov_b32_e32 v18, v176
	s_waitcnt vmcnt(0) lgkmcnt(0)
	v_mul_f32_e32 v17, v17, v18
	v_bfe_u32 v18, v17, 16, 1
	v_add3_u32 v18, v17, v18, s34
	ds_write_b32 v106, v17
	v_ashrrev_i32_e32 v17, 31, v16
	v_and_b32_e32 v18, 0xffff0000, v18
	v_lshlrev_b64 v[16:17], 2, v[16:17]
	v_add_f32_e32 v20, v22, v18
	v_lshl_add_u64 v[18:19], s[8:9], 0, v[16:17]
	v_lshl_add_u64 v[16:17], s[6:7], 0, v[16:17]
	v_mov_b32_e32 v18, v179
	s_waitcnt vmcnt(0) lgkmcnt(0)
	v_fmac_f32_e32 v74, v15, v18
	v_mov_b32_e32 v16, v178
	s_waitcnt vmcnt(0) lgkmcnt(0)
	v_mul_f32_e32 v15, v15, v16
	v_bfe_u32 v16, v15, 16, 1
	v_add3_u32 v16, v15, v16, s34
	ds_write_b32 v107, v15
	v_ashrrev_i32_e32 v15, 31, v14
	v_and_b32_e32 v16, 0xffff0000, v16
	v_lshlrev_b64 v[14:15], 2, v[14:15]
	v_add_f32_e32 v18, v20, v16
	v_lshl_add_u64 v[16:17], s[8:9], 0, v[14:15]
	v_lshl_add_u64 v[14:15], s[6:7], 0, v[14:15]
	v_mov_b32_e32 v14, v180
	s_waitcnt vmcnt(0) lgkmcnt(0)
	v_mul_f32_e32 v15, v113, v14
	v_mov_b32_e32 v16, v181
	ds_write_b32 v108, v15
	v_bfe_u32 v14, v15, 16, 1
	v_add3_u32 v14, v15, v14, s34
	v_and_b32_e32 v14, 0xffff0000, v14
	v_add_f32_e32 v14, v18, v14
	s_waitcnt vmcnt(0) lgkmcnt(0)
	v_fmac_f32_e32 v74, v113, v16
	v_lshl_add_u64 v[16:17], s[8:9], 0, v[12:13]
	v_lshl_add_u64 v[12:13], s[6:7], 0, v[12:13]
	v_mov_b32_e32 v12, v182
	s_waitcnt vmcnt(0) lgkmcnt(0)
	v_mul_f32_e32 v13, v112, v12
	v_mov_b32_e32 v15, v183
	v_bfe_u32 v12, v13, 16, 1
	v_add3_u32 v12, v13, v12, s34
	v_and_b32_e32 v12, 0xffff0000, v12
	v_add_f32_e32 v12, v14, v12
	ds_write_b32 v109, v13
	ds_bpermute_b32 v13, v110, v12
	s_waitcnt vmcnt(0) lgkmcnt(0)
	v_fmac_f32_e32 v74, v112, v15
	ds_bpermute_b32 v14, v110, v74
	s_and_saveexec_b64 s[14:15], vcc
	s_cbranch_execz .LBB0_959
	v_add_f32_e32 v12, v12, v13
	v_mul_f32_e32 v12, 0x4f800000, v12
	s_waitcnt lgkmcnt(0)
	v_add_f32_e32 v16, v74, v14
	v_rndne_f32_e32 v14, v12
	s_mov_b32 s3, 0x2f800000
	s_ashr_i32 s11, s10, 31
	v_mul_f32_e64 v12, |v14|, s3
	s_lshl_b64 s[20:21], s[10:11], 3
	v_floor_f32_e32 v12, v12
	s_mov_b32 s11, 0xcf800000
	v_fma_f32 v13, v12, s11, |v14|
	v_cvt_u32_f32_e32 v17, v13
	v_cvt_u32_f32_e32 v15, v12
	v_ashrrev_i32_e32 v18, 31, v14
	v_lshl_add_u64 v[12:13], v[6:7], 0, s[20:21]
	v_xor_b32_e32 v14, v17, v18
	v_xor_b32_e32 v15, v15, v18
	v_sub_co_u32_e64 v14, s[0:1], v14, v18
	s_nop 1
	v_subb_co_u32_e64 v15, s[0:1], v15, v18, s[0:1]
	flat_atomic_add_x2 v[12:13], v[14:15]
	v_mul_f32_e32 v12, 0x4f800000, v16
	v_rndne_f32_e32 v14, v12
	v_mul_f32_e64 v12, |v14|, s3
	v_floor_f32_e32 v12, v12
	v_fma_f32 v13, v12, s11, |v14|
	v_cvt_u32_f32_e32 v16, v13
	v_cvt_u32_f32_e32 v15, v12
	v_ashrrev_i32_e32 v17, 31, v14
	v_lshl_add_u64 v[12:13], v[8:9], 0, s[20:21]
	v_xor_b32_e32 v14, v16, v17
	v_xor_b32_e32 v15, v15, v17
	v_sub_co_u32_e64 v14, s[0:1], v14, v17
	s_nop 1
	v_subb_co_u32_e64 v15, s[0:1], v15, v17, s[0:1]
	flat_atomic_add_x2 v[12:13], v[14:15]
	s_branch .LBB0_959

.LBB0_1165:
	s_or_b64 exec, exec, s[14:15]
	s_andn2_b64 vcc, exec, s[10:11]
	s_cbranch_vccnz .LBB0_1169
	v_ashrrev_i32_e32 v17, 31, v16
	v_lshlrev_b64 v[16:17], 2, v[16:17]
	v_lshl_add_u64 v[18:19], s[8:9], 0, v[16:17]
	v_lshl_add_u64 v[16:17], s[6:7], 0, v[16:17]
	global_load_dword v16, v[16:17], off
	s_ashr_i32 s13, s12, 31
	global_load_dword v18, v[18:19], off
	s_waitcnt vmcnt(0) lgkmcnt(0)
	v_mul_f32_e32 v16, v57, v16
	v_bfe_u32 v17, v16, 16, 1
	v_add3_u32 v17, v16, v17, s34
	v_and_b32_e32 v17, 0xffff0000, v17
	v_add_f32_e32 v89, 0, v17
	ds_write_b32 v7, v16
	v_lshl_add_u64 v[16:17], s[12:13], 0, v[4:5]
	v_fma_f32 v88, v57, v18, 0
	v_lshlrev_b64 v[18:19], 2, v[16:17]
	v_lshl_add_u64 v[16:17], s[8:9], 0, v[18:19]
	global_load_dword v90, v[16:17], off offset:8
	v_lshl_add_u64 v[18:19], s[6:7], 0, v[18:19]
	global_load_dword v120, v[18:19], off offset:8
	global_load_dword v121, v[16:17], off offset:16
	global_load_dword v122, v[18:19], off offset:16
	global_load_dword v123, v[16:17], off offset:24
	global_load_dword v124, v[18:19], off offset:24
	global_load_dword v125, v[16:17], off offset:32
	global_load_dword v126, v[18:19], off offset:32
	global_load_dword v127, v[16:17], off offset:40
	global_load_dword v128, v[18:19], off offset:40
	global_load_dword v129, v[16:17], off offset:48
	global_load_dword v130, v[18:19], off offset:48
	global_load_dword v131, v[16:17], off offset:56
	global_load_dword v132, v[18:19], off offset:56
	global_load_dword v133, v[16:17], off offset:64
	global_load_dword v134, v[18:19], off offset:64
	global_load_dword v135, v[16:17], off offset:72
	global_load_dword v136, v[18:19], off offset:72
	global_load_dword v137, v[16:17], off offset:80
	global_load_dword v138, v[18:19], off offset:80
	global_load_dword v139, v[16:17], off offset:88
	global_load_dword v140, v[18:19], off offset:88
	global_load_dword v141, v[16:17], off offset:96
	global_load_dword v142, v[18:19], off offset:96
	global_load_dword v143, v[16:17], off offset:104
	global_load_dword v144, v[18:19], off offset:104
	global_load_dword v145, v[16:17], off offset:112
	global_load_dword v146, v[18:19], off offset:112
	global_load_dword v147, v[16:17], off offset:120
	global_load_dword v148, v[18:19], off offset:120
	global_load_dword v149, v[16:17], off offset:128
	global_load_dword v150, v[18:19], off offset:128
	global_load_dword v151, v[16:17], off offset:136
	global_load_dword v152, v[18:19], off offset:136
	global_load_dword v153, v[16:17], off offset:144
	global_load_dword v154, v[18:19], off offset:144
	global_load_dword v155, v[16:17], off offset:152
	global_load_dword v156, v[18:19], off offset:152
	global_load_dword v157, v[16:17], off offset:160
	global_load_dword v158, v[18:19], off offset:160
	global_load_dword v159, v[16:17], off offset:168
	global_load_dword v160, v[18:19], off offset:168
	global_load_dword v161, v[16:17], off offset:176
	global_load_dword v162, v[18:19], off offset:176
	global_load_dword v163, v[16:17], off offset:184
	global_load_dword v164, v[18:19], off offset:184
	global_load_dword v165, v[16:17], off offset:192
	global_load_dword v166, v[18:19], off offset:192
	global_load_dword v167, v[16:17], off offset:200
	global_load_dword v168, v[18:19], off offset:200
	global_load_dword v169, v[16:17], off offset:208
	global_load_dword v170, v[18:19], off offset:208
	global_load_dword v171, v[16:17], off offset:216
	global_load_dword v172, v[18:19], off offset:216
	global_load_dword v173, v[16:17], off offset:224
	global_load_dword v174, v[18:19], off offset:224
	global_load_dword v175, v[16:17], off offset:232
	global_load_dword v176, v[18:19], off offset:232
	global_load_dword v177, v[16:17], off offset:240
	global_load_dword v178, v[18:19], off offset:240
	s_waitcnt vmcnt(0)
	s_waitcnt vmcnt(0) lgkmcnt(0)
	v_fmac_f32_e32 v88, v56, v90
	v_mov_b32_e32 v90, v120
	s_waitcnt vmcnt(0) lgkmcnt(0)
	v_mul_f32_e32 v90, v56, v90
	v_bfe_u32 v91, v90, 16, 1
	ds_write_b32 v24, v90
	v_add3_u32 v91, v90, v91, s34
	v_mov_b32_e32 v90, v121
	v_and_b32_e32 v91, 0xffff0000, v91
	v_add_f32_e32 v89, v89, v91
	s_waitcnt vmcnt(0) lgkmcnt(0)
	v_fmac_f32_e32 v88, v59, v90
	v_mov_b32_e32 v90, v122
	s_waitcnt vmcnt(0) lgkmcnt(0)
	v_mul_f32_e32 v90, v59, v90
	v_bfe_u32 v91, v90, 16, 1
	ds_write_b32 v25, v90
	v_add3_u32 v91, v90, v91, s34
	v_mov_b32_e32 v90, v123
	v_and_b32_e32 v91, 0xffff0000, v91
	v_add_f32_e32 v89, v89, v91
	s_waitcnt vmcnt(0) lgkmcnt(0)
	v_fmac_f32_e32 v88, v58, v90
	v_mov_b32_e32 v90, v124
	s_waitcnt vmcnt(0) lgkmcnt(0)
	v_mul_f32_e32 v90, v58, v90
	v_bfe_u32 v91, v90, 16, 1
	ds_write_b32 v26, v90
	v_add3_u32 v91, v90, v91, s34
	v_mov_b32_e32 v90, v125
	v_and_b32_e32 v91, 0xffff0000, v91
	v_add_f32_e32 v89, v89, v91
	s_waitcnt vmcnt(0) lgkmcnt(0)
	v_fmac_f32_e32 v88, v61, v90
	v_mov_b32_e32 v90, v126
	s_waitcnt vmcnt(0) lgkmcnt(0)
	v_mul_f32_e32 v90, v61, v90
	v_bfe_u32 v91, v90, 16, 1
	ds_write_b32 v27, v90
	v_add3_u32 v91, v90, v91, s34
	v_mov_b32_e32 v90, v127
	v_and_b32_e32 v91, 0xffff0000, v91
	v_add_f32_e32 v89, v89, v91
	s_waitcnt vmcnt(0) lgkmcnt(0)
	v_fmac_f32_e32 v88, v60, v90
	v_mov_b32_e32 v90, v128
	s_waitcnt vmcnt(0) lgkmcnt(0)
	v_mul_f32_e32 v90, v60, v90
	v_bfe_u32 v91, v90, 16, 1
	ds_write_b32 v28, v90
	v_add3_u32 v91, v90, v91, s34
	v_mov_b32_e32 v90, v129
	v_and_b32_e32 v91, 0xffff0000, v91
	v_add_f32_e32 v89, v89, v91
	s_waitcnt vmcnt(0) lgkmcnt(0)
	v_fmac_f32_e32 v88, v63, v90
	v_mov_b32_e32 v90, v130
	s_waitcnt vmcnt(0) lgkmcnt(0)
	v_mul_f32_e32 v90, v63, v90
	v_bfe_u32 v91, v90, 16, 1
	ds_write_b32 v29, v90
	v_add3_u32 v91, v90, v91, s34
	v_mov_b32_e32 v90, v131
	v_and_b32_e32 v91, 0xffff0000, v91
	v_add_f32_e32 v89, v89, v91
	s_waitcnt vmcnt(0) lgkmcnt(0)
	v_fmac_f32_e32 v88, v62, v90
	v_mov_b32_e32 v90, v132
	s_waitcnt vmcnt(0) lgkmcnt(0)
	v_mul_f32_e32 v90, v62, v90
	v_bfe_u32 v91, v90, 16, 1
	ds_write_b32 v30, v90
	v_add3_u32 v91, v90, v91, s34
	v_mov_b32_e32 v90, v133
	v_and_b32_e32 v91, 0xffff0000, v91
	v_add_f32_e32 v89, v89, v91
	s_waitcnt vmcnt(0) lgkmcnt(0)
	v_fmac_f32_e32 v88, v65, v90
	v_mov_b32_e32 v90, v134
	s_waitcnt vmcnt(0) lgkmcnt(0)
	v_mul_f32_e32 v90, v65, v90
	v_bfe_u32 v91, v90, 16, 1
	ds_write_b32 v31, v90
	v_add3_u32 v91, v90, v91, s34
	v_mov_b32_e32 v90, v135
	v_and_b32_e32 v91, 0xffff0000, v91
	v_add_f32_e32 v89, v89, v91
	s_waitcnt vmcnt(0) lgkmcnt(0)
	v_fmac_f32_e32 v88, v64, v90
	v_mov_b32_e32 v90, v136
	s_waitcnt vmcnt(0) lgkmcnt(0)
	v_mul_f32_e32 v90, v64, v90
	v_bfe_u32 v91, v90, 16, 1
	ds_write_b32 v32, v90
	v_add3_u32 v91, v90, v91, s34
	v_mov_b32_e32 v90, v137
	v_and_b32_e32 v91, 0xffff0000, v91
	v_add_f32_e32 v89, v89, v91
	s_waitcnt vmcnt(0) lgkmcnt(0)
	v_fmac_f32_e32 v88, v67, v90
	v_mov_b32_e32 v90, v138
	s_waitcnt vmcnt(0) lgkmcnt(0)
	v_mul_f32_e32 v90, v67, v90
	v_bfe_u32 v91, v90, 16, 1
	ds_write_b32 v33, v90
	v_add3_u32 v91, v90, v91, s34
	v_mov_b32_e32 v90, v139
	v_and_b32_e32 v91, 0xffff0000, v91
	v_add_f32_e32 v89, v89, v91
	s_waitcnt vmcnt(0) lgkmcnt(0)
	v_fmac_f32_e32 v88, v66, v90
	v_mov_b32_e32 v90, v140
	s_waitcnt vmcnt(0) lgkmcnt(0)
	v_mul_f32_e32 v90, v66, v90
	v_bfe_u32 v91, v90, 16, 1
	ds_write_b32 v34, v90
	v_add3_u32 v91, v90, v91, s34
	v_mov_b32_e32 v90, v141
	v_and_b32_e32 v91, 0xffff0000, v91
	v_add_f32_e32 v89, v89, v91
	s_waitcnt vmcnt(0) lgkmcnt(0)
	v_fmac_f32_e32 v88, v69, v90
	v_mov_b32_e32 v90, v142
	s_waitcnt vmcnt(0) lgkmcnt(0)
	v_mul_f32_e32 v90, v69, v90
	v_bfe_u32 v91, v90, 16, 1
	ds_write_b32 v35, v90
	v_add3_u32 v91, v90, v91, s34
	v_mov_b32_e32 v90, v143
	v_and_b32_e32 v91, 0xffff0000, v91
	v_add_f32_e32 v89, v89, v91
	s_waitcnt vmcnt(0) lgkmcnt(0)
	v_fmac_f32_e32 v88, v68, v90
	v_mov_b32_e32 v90, v144
	s_waitcnt vmcnt(0) lgkmcnt(0)
	v_mul_f32_e32 v90, v68, v90
	v_bfe_u32 v91, v90, 16, 1
	ds_write_b32 v36, v90
	v_add3_u32 v91, v90, v91, s34
	v_mov_b32_e32 v90, v145
	v_and_b32_e32 v91, 0xffff0000, v91
	v_add_f32_e32 v89, v89, v91
	s_waitcnt vmcnt(0) lgkmcnt(0)
	v_fmac_f32_e32 v88, v71, v90
	v_mov_b32_e32 v90, v146
	s_waitcnt vmcnt(0) lgkmcnt(0)
	v_mul_f32_e32 v90, v71, v90
	v_bfe_u32 v91, v90, 16, 1
	ds_write_b32 v37, v90
	v_add3_u32 v91, v90, v91, s34
	v_mov_b32_e32 v90, v147
	v_and_b32_e32 v91, 0xffff0000, v91
	v_add_f32_e32 v89, v89, v91
	s_waitcnt vmcnt(0) lgkmcnt(0)
	v_fmac_f32_e32 v88, v70, v90
	v_mov_b32_e32 v90, v148
	s_waitcnt vmcnt(0) lgkmcnt(0)
	v_mul_f32_e32 v90, v70, v90
	v_bfe_u32 v91, v90, 16, 1
	ds_write_b32 v38, v90
	v_add3_u32 v91, v90, v91, s34
	v_mov_b32_e32 v90, v149
	v_and_b32_e32 v91, 0xffff0000, v91
	v_add_f32_e32 v89, v89, v91
	s_waitcnt vmcnt(0) lgkmcnt(0)
	v_fmac_f32_e32 v88, v73, v90
	v_mov_b32_e32 v90, v150
	s_waitcnt vmcnt(0) lgkmcnt(0)
	v_mul_f32_e32 v90, v73, v90
	v_bfe_u32 v91, v90, 16, 1
	ds_write_b32 v39, v90
	v_add3_u32 v91, v90, v91, s34
	v_mov_b32_e32 v90, v151
	v_and_b32_e32 v91, 0xffff0000, v91
	v_add_f32_e32 v89, v89, v91
	s_waitcnt vmcnt(0) lgkmcnt(0)
	v_fmac_f32_e32 v88, v72, v90
	v_mov_b32_e32 v90, v152
	s_waitcnt vmcnt(0) lgkmcnt(0)
	v_mul_f32_e32 v90, v72, v90
	v_bfe_u32 v91, v90, 16, 1
	ds_write_b32 v40, v90
	v_add3_u32 v91, v90, v91, s34
	v_mov_b32_e32 v90, v153
	v_and_b32_e32 v91, 0xffff0000, v91
	v_add_f32_e32 v89, v89, v91
	s_waitcnt vmcnt(0) lgkmcnt(0)
	v_fmac_f32_e32 v88, v75, v90
	v_mov_b32_e32 v90, v154
	s_waitcnt vmcnt(0) lgkmcnt(0)
	v_mul_f32_e32 v90, v75, v90
	v_bfe_u32 v91, v90, 16, 1
	ds_write_b32 v41, v90
	v_add3_u32 v91, v90, v91, s34
	v_mov_b32_e32 v90, v155
	v_and_b32_e32 v91, 0xffff0000, v91
	v_add_f32_e32 v89, v89, v91
	s_waitcnt vmcnt(0) lgkmcnt(0)
	v_fmac_f32_e32 v88, v74, v90
	v_mov_b32_e32 v90, v156
	s_waitcnt vmcnt(0) lgkmcnt(0)
	v_mul_f32_e32 v90, v74, v90
	v_bfe_u32 v91, v90, 16, 1
	ds_write_b32 v42, v90
	v_add3_u32 v91, v90, v91, s34
	v_mov_b32_e32 v90, v157
	v_and_b32_e32 v91, 0xffff0000, v91
	v_add_f32_e32 v89, v89, v91
	s_waitcnt vmcnt(0) lgkmcnt(0)
	v_fmac_f32_e32 v88, v77, v90
	v_mov_b32_e32 v90, v158
	s_waitcnt vmcnt(0) lgkmcnt(0)
	v_mul_f32_e32 v90, v77, v90
	v_bfe_u32 v91, v90, 16, 1
	ds_write_b32 v43, v90
	v_add3_u32 v91, v90, v91, s34
	v_mov_b32_e32 v90, v159
	v_and_b32_e32 v91, 0xffff0000, v91
	v_add_f32_e32 v89, v89, v91
	s_waitcnt vmcnt(0) lgkmcnt(0)
	v_fmac_f32_e32 v88, v76, v90
	v_mov_b32_e32 v90, v160
	s_waitcnt vmcnt(0) lgkmcnt(0)
	v_mul_f32_e32 v90, v76, v90
	v_bfe_u32 v91, v90, 16, 1
	ds_write_b32 v44, v90
	v_add3_u32 v91, v90, v91, s34
	v_mov_b32_e32 v90, v161
	v_and_b32_e32 v91, 0xffff0000, v91
	v_add_f32_e32 v89, v89, v91
	s_waitcnt vmcnt(0) lgkmcnt(0)
	v_fmac_f32_e32 v88, v79, v90
	v_mov_b32_e32 v90, v162
	s_waitcnt vmcnt(0) lgkmcnt(0)
	v_mul_f32_e32 v90, v79, v90
	v_bfe_u32 v91, v90, 16, 1
	ds_write_b32 v45, v90
	v_add3_u32 v91, v90, v91, s34
	v_mov_b32_e32 v90, v163
	v_and_b32_e32 v91, 0xffff0000, v91
	v_add_f32_e32 v89, v89, v91
	s_waitcnt vmcnt(0) lgkmcnt(0)
	v_fmac_f32_e32 v88, v78, v90
	v_mov_b32_e32 v90, v164
	s_waitcnt vmcnt(0) lgkmcnt(0)
	v_mul_f32_e32 v90, v78, v90
	v_bfe_u32 v91, v90, 16, 1
	ds_write_b32 v46, v90
	v_add3_u32 v91, v90, v91, s34
	v_mov_b32_e32 v90, v165
	v_and_b32_e32 v91, 0xffff0000, v91
	v_add_f32_e32 v89, v89, v91
	s_waitcnt vmcnt(0) lgkmcnt(0)
	v_fmac_f32_e32 v88, v81, v90
	v_mov_b32_e32 v90, v166
	s_waitcnt vmcnt(0) lgkmcnt(0)
	v_mul_f32_e32 v90, v81, v90
	v_bfe_u32 v91, v90, 16, 1
	ds_write_b32 v47, v90
	v_add3_u32 v91, v90, v91, s34
	v_mov_b32_e32 v90, v167
	v_and_b32_e32 v91, 0xffff0000, v91
	v_add_f32_e32 v89, v89, v91
	s_waitcnt vmcnt(0) lgkmcnt(0)
	v_fmac_f32_e32 v88, v80, v90
	v_mov_b32_e32 v90, v168
	s_waitcnt vmcnt(0) lgkmcnt(0)
	v_mul_f32_e32 v90, v80, v90
	v_bfe_u32 v91, v90, 16, 1
	ds_write_b32 v48, v90
	v_add3_u32 v91, v90, v91, s34
	v_mov_b32_e32 v90, v169
	v_and_b32_e32 v91, 0xffff0000, v91
	v_add_f32_e32 v89, v89, v91
	s_waitcnt vmcnt(0) lgkmcnt(0)
	v_fmac_f32_e32 v88, v83, v90
	v_mov_b32_e32 v90, v170
	s_waitcnt vmcnt(0) lgkmcnt(0)
	v_mul_f32_e32 v90, v83, v90
	v_bfe_u32 v91, v90, 16, 1
	ds_write_b32 v49, v90
	v_add3_u32 v91, v90, v91, s34
	v_mov_b32_e32 v90, v171
	v_and_b32_e32 v91, 0xffff0000, v91
	v_add_f32_e32 v89, v89, v91
	s_waitcnt vmcnt(0) lgkmcnt(0)
	v_fmac_f32_e32 v88, v82, v90
	v_mov_b32_e32 v90, v172
	s_waitcnt vmcnt(0) lgkmcnt(0)
	v_mul_f32_e32 v90, v82, v90
	v_bfe_u32 v91, v90, 16, 1
	ds_write_b32 v50, v90
	v_add3_u32 v91, v90, v91, s34
	v_mov_b32_e32 v90, v173
	v_and_b32_e32 v91, 0xffff0000, v91
	v_add_f32_e32 v89, v89, v91
	s_waitcnt vmcnt(0) lgkmcnt(0)
	v_fmac_f32_e32 v88, v85, v90
	v_mov_b32_e32 v90, v174
	s_waitcnt vmcnt(0) lgkmcnt(0)
	v_mul_f32_e32 v90, v85, v90
	v_bfe_u32 v91, v90, 16, 1
	ds_write_b32 v51, v90
	v_add3_u32 v91, v90, v91, s34
	v_mov_b32_e32 v90, v175
	v_and_b32_e32 v91, 0xffff0000, v91
	v_add_f32_e32 v89, v89, v91
	s_waitcnt vmcnt(0) lgkmcnt(0)
	v_fmac_f32_e32 v88, v84, v90
	v_mov_b32_e32 v90, v176
	s_waitcnt vmcnt(0) lgkmcnt(0)
	v_mul_f32_e32 v90, v84, v90
	v_bfe_u32 v91, v90, 16, 1
	ds_write_b32 v52, v90
	v_add3_u32 v91, v90, v91, s34
	v_mov_b32_e32 v90, v177
	v_and_b32_e32 v91, 0xffff0000, v91
	v_add_f32_e32 v89, v89, v91
	s_waitcnt vmcnt(0) lgkmcnt(0)
	v_fmac_f32_e32 v88, v87, v90
	v_mov_b32_e32 v90, v178
	s_waitcnt vmcnt(0) lgkmcnt(0)
	v_mul_f32_e32 v90, v87, v90
	ds_write_b32 v53, v90
	global_load_dword v16, v[16:17], off offset:248
	v_bfe_u32 v91, v90, 16, 1
	v_add3_u32 v91, v90, v91, s34
	v_and_b32_e32 v91, 0xffff0000, v91
	v_add_f32_e32 v89, v89, v91
	s_waitcnt vmcnt(0) lgkmcnt(0)
	v_fmac_f32_e32 v88, v86, v16
	global_load_dword v16, v[18:19], off offset:248
	ds_bpermute_b32 v18, v55, v88
	s_waitcnt vmcnt(0) lgkmcnt(0)
	v_mul_f32_e32 v17, v86, v16
	v_bfe_u32 v16, v17, 16, 1
	v_add3_u32 v16, v17, v16, s34
	v_and_b32_e32 v16, 0xffff0000, v16
	v_add_f32_e32 v16, v89, v16
	ds_write_b32 v54, v17
	ds_bpermute_b32 v17, v55, v16
	s_and_saveexec_b64 s[14:15], s[0:1]
	s_cbranch_execz .LBB0_1168
	s_waitcnt lgkmcnt(0)
	v_add_f32_e32 v16, v16, v17
	v_mul_f32_e32 v16, 0x4f800000, v16
	v_add_f32_e32 v88, v88, v18
	v_rndne_f32_e32 v18, v16
	s_mov_b32 s3, 0x2f800000
	s_ashr_i32 s5, s4, 31
	v_mul_f32_e64 v16, |v18|, s3
	s_lshl_b64 s[16:17], s[4:5], 3
	v_floor_f32_e32 v16, v16
	s_mov_b32 s5, 0xcf800000
	v_fma_f32 v17, v16, s5, |v18|
	v_cvt_u32_f32_e32 v89, v17
	v_cvt_u32_f32_e32 v19, v16
	v_ashrrev_i32_e32 v90, 31, v18
	v_lshl_add_u64 v[16:17], v[10:11], 0, s[16:17]
	v_xor_b32_e32 v18, v89, v90
	v_xor_b32_e32 v19, v19, v90
	v_sub_co_u32_e32 v18, vcc, v18, v90
	s_nop 1
	v_subb_co_u32_e32 v19, vcc, v19, v90, vcc
	flat_atomic_add_x2 v[16:17], v[18:19]
	v_mul_f32_e32 v16, 0x4f800000, v88
	v_rndne_f32_e32 v18, v16
	v_mul_f32_e64 v16, |v18|, s3
	v_floor_f32_e32 v16, v16
	v_fma_f32 v17, v16, s5, |v18|
	v_cvt_u32_f32_e32 v88, v17
	v_cvt_u32_f32_e32 v19, v16
	v_ashrrev_i32_e32 v89, 31, v18
	v_lshl_add_u64 v[16:17], v[12:13], 0, s[16:17]
	v_xor_b32_e32 v18, v88, v89
	v_xor_b32_e32 v19, v19, v89
	v_sub_co_u32_e32 v18, vcc, v18, v89
	s_nop 1
	v_subb_co_u32_e32 v19, vcc, v19, v89, vcc
	flat_atomic_add_x2 v[16:17], v[18:19]

.LBB0_1310:
	v_ashrrev_i32_e32 v15, 31, v14
	v_readlane_b32 s10, v254, 59
	v_lshlrev_b64 v[16:17], 2, v[14:15]
	v_readlane_b32 s11, v254, 60
	s_nop 1
	v_lshl_add_u64 v[14:15], s[10:11], 0, v[16:17]
	v_lshl_add_u64 v[16:17], s[20:21], 0, v[16:17]
	global_load_dword v86, v[16:17], off
	global_load_dword v85, v[14:15], off
	s_waitcnt vmcnt(0) lgkmcnt(0)
	v_mul_f32_e32 v86, v54, v86
	v_bfe_u32 v87, v86, 16, 1
	ds_write_b32 v5, v86
	v_add3_u32 v87, v86, v87, s34
	global_load_dword v120, v[14:15], off offset:8
	global_load_dword v121, v[16:17], off offset:8
	global_load_dword v122, v[14:15], off offset:16
	global_load_dword v123, v[16:17], off offset:16
	global_load_dword v124, v[14:15], off offset:24
	global_load_dword v125, v[16:17], off offset:24
	global_load_dword v126, v[14:15], off offset:32
	global_load_dword v127, v[16:17], off offset:32
	global_load_dword v128, v[14:15], off offset:40
	global_load_dword v129, v[16:17], off offset:40
	global_load_dword v130, v[14:15], off offset:48
	global_load_dword v131, v[16:17], off offset:48
	global_load_dword v132, v[14:15], off offset:56
	global_load_dword v133, v[16:17], off offset:56
	global_load_dword v134, v[14:15], off offset:64
	global_load_dword v135, v[16:17], off offset:64
	global_load_dword v136, v[14:15], off offset:72
	global_load_dword v137, v[16:17], off offset:72
	global_load_dword v138, v[14:15], off offset:80
	global_load_dword v139, v[16:17], off offset:80
	global_load_dword v140, v[14:15], off offset:88
	global_load_dword v141, v[16:17], off offset:88
	global_load_dword v142, v[14:15], off offset:96
	global_load_dword v143, v[16:17], off offset:96
	global_load_dword v144, v[14:15], off offset:104
	global_load_dword v145, v[16:17], off offset:104
	global_load_dword v146, v[14:15], off offset:112
	global_load_dword v147, v[16:17], off offset:112
	global_load_dword v148, v[14:15], off offset:120
	global_load_dword v149, v[16:17], off offset:120
	global_load_dword v150, v[14:15], off offset:128
	global_load_dword v151, v[16:17], off offset:128
	global_load_dword v152, v[14:15], off offset:136
	global_load_dword v153, v[16:17], off offset:136
	global_load_dword v154, v[14:15], off offset:144
	global_load_dword v155, v[16:17], off offset:144
	global_load_dword v156, v[14:15], off offset:152
	global_load_dword v157, v[16:17], off offset:152
	global_load_dword v158, v[14:15], off offset:160
	global_load_dword v159, v[16:17], off offset:160
	global_load_dword v160, v[14:15], off offset:168
	global_load_dword v161, v[16:17], off offset:168
	global_load_dword v162, v[14:15], off offset:176
	global_load_dword v163, v[16:17], off offset:176
	global_load_dword v164, v[14:15], off offset:184
	global_load_dword v165, v[16:17], off offset:184
	global_load_dword v166, v[14:15], off offset:192
	global_load_dword v167, v[16:17], off offset:192
	global_load_dword v168, v[14:15], off offset:200
	global_load_dword v169, v[16:17], off offset:200
	global_load_dword v170, v[14:15], off offset:208
	global_load_dword v171, v[16:17], off offset:208
	global_load_dword v172, v[14:15], off offset:216
	global_load_dword v173, v[16:17], off offset:216
	global_load_dword v174, v[14:15], off offset:224
	global_load_dword v175, v[16:17], off offset:224
	global_load_dword v176, v[14:15], off offset:232
	global_load_dword v177, v[16:17], off offset:232
	global_load_dword v178, v[14:15], off offset:240
	global_load_dword v179, v[16:17], off offset:240
	s_waitcnt vmcnt(0)
	v_mov_b32_e32 v86, v120
	v_fma_f32 v85, v54, v85, 0
	v_and_b32_e32 v87, 0xffff0000, v87
	v_add_f32_e32 v87, 0, v87
	s_waitcnt vmcnt(0) lgkmcnt(0)
	v_fmac_f32_e32 v85, v53, v86
	v_mov_b32_e32 v86, v121
	s_waitcnt vmcnt(0) lgkmcnt(0)
	v_mul_f32_e32 v86, v53, v86
	v_bfe_u32 v88, v86, 16, 1
	ds_write_b32 v7, v86
	v_add3_u32 v88, v86, v88, s34
	v_mov_b32_e32 v86, v122
	v_and_b32_e32 v88, 0xffff0000, v88
	v_add_f32_e32 v87, v87, v88
	s_waitcnt vmcnt(0) lgkmcnt(0)
	v_fmac_f32_e32 v85, v56, v86
	v_mov_b32_e32 v86, v123
	s_waitcnt vmcnt(0) lgkmcnt(0)
	v_mul_f32_e32 v86, v56, v86
	v_bfe_u32 v88, v86, 16, 1
	ds_write_b32 v18, v86
	v_add3_u32 v88, v86, v88, s34
	v_mov_b32_e32 v86, v124
	v_and_b32_e32 v88, 0xffff0000, v88
	v_add_f32_e32 v87, v87, v88
	s_waitcnt vmcnt(0) lgkmcnt(0)
	v_fmac_f32_e32 v85, v55, v86
	v_mov_b32_e32 v86, v125
	s_waitcnt vmcnt(0) lgkmcnt(0)
	v_mul_f32_e32 v86, v55, v86
	v_bfe_u32 v88, v86, 16, 1
	ds_write_b32 v19, v86
	v_add3_u32 v88, v86, v88, s34
	v_mov_b32_e32 v86, v126
	v_and_b32_e32 v88, 0xffff0000, v88
	v_add_f32_e32 v87, v87, v88
	s_waitcnt vmcnt(0) lgkmcnt(0)
	v_fmac_f32_e32 v85, v58, v86
	v_mov_b32_e32 v86, v127
	s_waitcnt vmcnt(0) lgkmcnt(0)
	v_mul_f32_e32 v86, v58, v86
	v_bfe_u32 v88, v86, 16, 1
	ds_write_b32 v24, v86
	v_add3_u32 v88, v86, v88, s34
	v_mov_b32_e32 v86, v128
	v_and_b32_e32 v88, 0xffff0000, v88
	v_add_f32_e32 v87, v87, v88
	s_waitcnt vmcnt(0) lgkmcnt(0)
	v_fmac_f32_e32 v85, v57, v86
	v_mov_b32_e32 v86, v129
	s_waitcnt vmcnt(0) lgkmcnt(0)
	v_mul_f32_e32 v86, v57, v86
	v_bfe_u32 v88, v86, 16, 1
	ds_write_b32 v25, v86
	v_add3_u32 v88, v86, v88, s34
	v_mov_b32_e32 v86, v130
	v_and_b32_e32 v88, 0xffff0000, v88
	v_add_f32_e32 v87, v87, v88
	s_waitcnt vmcnt(0) lgkmcnt(0)
	v_fmac_f32_e32 v85, v60, v86
	v_mov_b32_e32 v86, v131
	s_waitcnt vmcnt(0) lgkmcnt(0)
	v_mul_f32_e32 v86, v60, v86
	v_bfe_u32 v88, v86, 16, 1
	ds_write_b32 v26, v86
	v_add3_u32 v88, v86, v88, s34
	v_mov_b32_e32 v86, v132
	v_and_b32_e32 v88, 0xffff0000, v88
	v_add_f32_e32 v87, v87, v88
	s_waitcnt vmcnt(0) lgkmcnt(0)
	v_fmac_f32_e32 v85, v59, v86
	v_mov_b32_e32 v86, v133
	s_waitcnt vmcnt(0) lgkmcnt(0)
	v_mul_f32_e32 v86, v59, v86
	v_bfe_u32 v88, v86, 16, 1
	ds_write_b32 v27, v86
	v_add3_u32 v88, v86, v88, s34
	v_mov_b32_e32 v86, v134
	v_and_b32_e32 v88, 0xffff0000, v88
	v_add_f32_e32 v87, v87, v88
	s_waitcnt vmcnt(0) lgkmcnt(0)
	v_fmac_f32_e32 v85, v62, v86
	v_mov_b32_e32 v86, v135
	s_waitcnt vmcnt(0) lgkmcnt(0)
	v_mul_f32_e32 v86, v62, v86
	v_bfe_u32 v88, v86, 16, 1
	ds_write_b32 v28, v86
	v_add3_u32 v88, v86, v88, s34
	v_mov_b32_e32 v86, v136
	v_and_b32_e32 v88, 0xffff0000, v88
	v_add_f32_e32 v87, v87, v88
	s_waitcnt vmcnt(0) lgkmcnt(0)
	v_fmac_f32_e32 v85, v61, v86
	v_mov_b32_e32 v86, v137
	s_waitcnt vmcnt(0) lgkmcnt(0)
	v_mul_f32_e32 v86, v61, v86
	v_bfe_u32 v88, v86, 16, 1
	ds_write_b32 v29, v86
	v_add3_u32 v88, v86, v88, s34
	v_mov_b32_e32 v86, v138
	v_and_b32_e32 v88, 0xffff0000, v88
	v_add_f32_e32 v87, v87, v88
	s_waitcnt vmcnt(0) lgkmcnt(0)
	v_fmac_f32_e32 v85, v64, v86
	v_mov_b32_e32 v86, v139
	s_waitcnt vmcnt(0) lgkmcnt(0)
	v_mul_f32_e32 v86, v64, v86
	v_bfe_u32 v88, v86, 16, 1
	ds_write_b32 v30, v86
	v_add3_u32 v88, v86, v88, s34
	v_mov_b32_e32 v86, v140
	v_and_b32_e32 v88, 0xffff0000, v88
	v_add_f32_e32 v87, v87, v88
	s_waitcnt vmcnt(0) lgkmcnt(0)
	v_fmac_f32_e32 v85, v63, v86
	v_mov_b32_e32 v86, v141
	s_waitcnt vmcnt(0) lgkmcnt(0)
	v_mul_f32_e32 v86, v63, v86
	v_bfe_u32 v88, v86, 16, 1
	ds_write_b32 v31, v86
	v_add3_u32 v88, v86, v88, s34
	v_mov_b32_e32 v86, v142
	v_and_b32_e32 v88, 0xffff0000, v88
	v_add_f32_e32 v87, v87, v88
	s_waitcnt vmcnt(0) lgkmcnt(0)
	v_fmac_f32_e32 v85, v66, v86
	v_mov_b32_e32 v86, v143
	s_waitcnt vmcnt(0) lgkmcnt(0)
	v_mul_f32_e32 v86, v66, v86
	v_bfe_u32 v88, v86, 16, 1
	ds_write_b32 v32, v86
	v_add3_u32 v88, v86, v88, s34
	v_mov_b32_e32 v86, v144
	v_and_b32_e32 v88, 0xffff0000, v88
	v_add_f32_e32 v87, v87, v88
	s_waitcnt vmcnt(0) lgkmcnt(0)
	v_fmac_f32_e32 v85, v65, v86
	v_mov_b32_e32 v86, v145
	s_waitcnt vmcnt(0) lgkmcnt(0)
	v_mul_f32_e32 v86, v65, v86
	v_bfe_u32 v88, v86, 16, 1
	ds_write_b32 v33, v86
	v_add3_u32 v88, v86, v88, s34
	v_mov_b32_e32 v86, v146
	v_and_b32_e32 v88, 0xffff0000, v88
	v_add_f32_e32 v87, v87, v88
	s_waitcnt vmcnt(0) lgkmcnt(0)
	v_fmac_f32_e32 v85, v68, v86
	v_mov_b32_e32 v86, v147
	s_waitcnt vmcnt(0) lgkmcnt(0)
	v_mul_f32_e32 v86, v68, v86
	v_bfe_u32 v88, v86, 16, 1
	ds_write_b32 v34, v86
	v_add3_u32 v88, v86, v88, s34
	v_mov_b32_e32 v86, v148
	v_and_b32_e32 v88, 0xffff0000, v88
	v_add_f32_e32 v87, v87, v88
	s_waitcnt vmcnt(0) lgkmcnt(0)
	v_fmac_f32_e32 v85, v67, v86
	v_mov_b32_e32 v86, v149
	s_waitcnt vmcnt(0) lgkmcnt(0)
	v_mul_f32_e32 v86, v67, v86
	v_bfe_u32 v88, v86, 16, 1
	ds_write_b32 v35, v86
	v_add3_u32 v88, v86, v88, s34
	v_mov_b32_e32 v86, v150
	v_and_b32_e32 v88, 0xffff0000, v88
	v_add_f32_e32 v87, v87, v88
	s_waitcnt vmcnt(0) lgkmcnt(0)
	v_fmac_f32_e32 v85, v70, v86
	v_mov_b32_e32 v86, v151
	s_waitcnt vmcnt(0) lgkmcnt(0)
	v_mul_f32_e32 v86, v70, v86
	v_bfe_u32 v88, v86, 16, 1
	ds_write_b32 v36, v86
	v_add3_u32 v88, v86, v88, s34
	v_mov_b32_e32 v86, v152
	v_and_b32_e32 v88, 0xffff0000, v88
	v_add_f32_e32 v87, v87, v88
	s_waitcnt vmcnt(0) lgkmcnt(0)
	v_fmac_f32_e32 v85, v69, v86
	v_mov_b32_e32 v86, v153
	s_waitcnt vmcnt(0) lgkmcnt(0)
	v_mul_f32_e32 v86, v69, v86
	v_bfe_u32 v88, v86, 16, 1
	ds_write_b32 v37, v86
	v_add3_u32 v88, v86, v88, s34
	v_mov_b32_e32 v86, v154
	v_and_b32_e32 v88, 0xffff0000, v88
	v_add_f32_e32 v87, v87, v88
	s_waitcnt vmcnt(0) lgkmcnt(0)
	v_fmac_f32_e32 v85, v72, v86
	v_mov_b32_e32 v86, v155
	s_waitcnt vmcnt(0) lgkmcnt(0)
	v_mul_f32_e32 v86, v72, v86
	v_bfe_u32 v88, v86, 16, 1
	ds_write_b32 v38, v86
	v_add3_u32 v88, v86, v88, s34
	v_mov_b32_e32 v86, v156
	v_and_b32_e32 v88, 0xffff0000, v88
	v_add_f32_e32 v87, v87, v88
	s_waitcnt vmcnt(0) lgkmcnt(0)
	v_fmac_f32_e32 v85, v71, v86
	v_mov_b32_e32 v86, v157
	s_waitcnt vmcnt(0) lgkmcnt(0)
	v_mul_f32_e32 v86, v71, v86
	v_bfe_u32 v88, v86, 16, 1
	ds_write_b32 v39, v86
	v_add3_u32 v88, v86, v88, s34
	v_mov_b32_e32 v86, v158
	v_and_b32_e32 v88, 0xffff0000, v88
	v_add_f32_e32 v87, v87, v88
	s_waitcnt vmcnt(0) lgkmcnt(0)
	v_fmac_f32_e32 v85, v74, v86
	v_mov_b32_e32 v86, v159
	s_waitcnt vmcnt(0) lgkmcnt(0)
	v_mul_f32_e32 v86, v74, v86
	v_bfe_u32 v88, v86, 16, 1
	ds_write_b32 v40, v86
	v_add3_u32 v88, v86, v88, s34
	v_mov_b32_e32 v86, v160
	v_and_b32_e32 v88, 0xffff0000, v88
	v_add_f32_e32 v87, v87, v88
	s_waitcnt vmcnt(0) lgkmcnt(0)
	v_fmac_f32_e32 v85, v73, v86
	v_mov_b32_e32 v86, v161
	s_waitcnt vmcnt(0) lgkmcnt(0)
	v_mul_f32_e32 v86, v73, v86
	v_bfe_u32 v88, v86, 16, 1
	ds_write_b32 v41, v86
	v_add3_u32 v88, v86, v88, s34
	v_mov_b32_e32 v86, v162
	v_and_b32_e32 v88, 0xffff0000, v88
	v_add_f32_e32 v87, v87, v88
	s_waitcnt vmcnt(0) lgkmcnt(0)
	v_fmac_f32_e32 v85, v76, v86
	v_mov_b32_e32 v86, v163
	s_waitcnt vmcnt(0) lgkmcnt(0)
	v_mul_f32_e32 v86, v76, v86
	v_bfe_u32 v88, v86, 16, 1
	ds_write_b32 v42, v86
	v_add3_u32 v88, v86, v88, s34
	v_mov_b32_e32 v86, v164
	v_and_b32_e32 v88, 0xffff0000, v88
	v_add_f32_e32 v87, v87, v88
	s_waitcnt vmcnt(0) lgkmcnt(0)
	v_fmac_f32_e32 v85, v75, v86
	v_mov_b32_e32 v86, v165
	s_waitcnt vmcnt(0) lgkmcnt(0)
	v_mul_f32_e32 v86, v75, v86
	v_bfe_u32 v88, v86, 16, 1
	ds_write_b32 v43, v86
	v_add3_u32 v88, v86, v88, s34
	v_mov_b32_e32 v86, v166
	v_and_b32_e32 v88, 0xffff0000, v88
	v_add_f32_e32 v87, v87, v88
	s_waitcnt vmcnt(0) lgkmcnt(0)
	v_fmac_f32_e32 v85, v78, v86
	v_mov_b32_e32 v86, v167
	s_waitcnt vmcnt(0) lgkmcnt(0)
	v_mul_f32_e32 v86, v78, v86
	v_bfe_u32 v88, v86, 16, 1
	ds_write_b32 v44, v86
	v_add3_u32 v88, v86, v88, s34
	v_mov_b32_e32 v86, v168
	v_and_b32_e32 v88, 0xffff0000, v88
	v_add_f32_e32 v87, v87, v88
	s_waitcnt vmcnt(0) lgkmcnt(0)
	v_fmac_f32_e32 v85, v77, v86
	v_mov_b32_e32 v86, v169
	s_waitcnt vmcnt(0) lgkmcnt(0)
	v_mul_f32_e32 v86, v77, v86
	v_bfe_u32 v88, v86, 16, 1
	ds_write_b32 v45, v86
	v_add3_u32 v88, v86, v88, s34
	v_mov_b32_e32 v86, v170
	v_and_b32_e32 v88, 0xffff0000, v88
	v_add_f32_e32 v87, v87, v88
	s_waitcnt vmcnt(0) lgkmcnt(0)
	v_fmac_f32_e32 v85, v80, v86
	v_mov_b32_e32 v86, v171
	s_waitcnt vmcnt(0) lgkmcnt(0)
	v_mul_f32_e32 v86, v80, v86
	v_bfe_u32 v88, v86, 16, 1
	ds_write_b32 v46, v86
	v_add3_u32 v88, v86, v88, s34
	v_mov_b32_e32 v86, v172
	v_and_b32_e32 v88, 0xffff0000, v88
	v_add_f32_e32 v87, v87, v88
	s_waitcnt vmcnt(0) lgkmcnt(0)
	v_fmac_f32_e32 v85, v79, v86
	v_mov_b32_e32 v86, v173
	s_waitcnt vmcnt(0) lgkmcnt(0)
	v_mul_f32_e32 v86, v79, v86
	v_bfe_u32 v88, v86, 16, 1
	ds_write_b32 v47, v86
	v_add3_u32 v88, v86, v88, s34
	v_mov_b32_e32 v86, v174
	v_and_b32_e32 v88, 0xffff0000, v88
	v_add_f32_e32 v87, v87, v88
	s_waitcnt vmcnt(0) lgkmcnt(0)
	v_fmac_f32_e32 v85, v82, v86
	v_mov_b32_e32 v86, v175
	s_waitcnt vmcnt(0) lgkmcnt(0)
	v_mul_f32_e32 v86, v82, v86
	v_bfe_u32 v88, v86, 16, 1
	ds_write_b32 v48, v86
	v_add3_u32 v88, v86, v88, s34
	v_mov_b32_e32 v86, v176
	v_and_b32_e32 v88, 0xffff0000, v88
	v_add_f32_e32 v87, v87, v88
	s_waitcnt vmcnt(0) lgkmcnt(0)
	v_fmac_f32_e32 v85, v81, v86
	v_mov_b32_e32 v86, v177
	s_waitcnt vmcnt(0) lgkmcnt(0)
	v_mul_f32_e32 v86, v81, v86
	v_bfe_u32 v88, v86, 16, 1
	ds_write_b32 v49, v86
	v_add3_u32 v88, v86, v88, s34
	v_mov_b32_e32 v86, v178
	v_and_b32_e32 v88, 0xffff0000, v88
	v_add_f32_e32 v87, v87, v88
	s_waitcnt vmcnt(0) lgkmcnt(0)
	v_fmac_f32_e32 v85, v84, v86
	v_mov_b32_e32 v86, v179
	s_waitcnt vmcnt(0) lgkmcnt(0)
	v_mul_f32_e32 v86, v84, v86
	ds_write_b32 v50, v86
	global_load_dword v14, v[14:15], off offset:248
	v_bfe_u32 v88, v86, 16, 1
	v_add3_u32 v88, v86, v88, s34
	v_and_b32_e32 v88, 0xffff0000, v88
	v_add_f32_e32 v87, v87, v88
	s_waitcnt vmcnt(0) lgkmcnt(0)
	v_fmac_f32_e32 v85, v83, v14
	global_load_dword v14, v[16:17], off offset:248
	ds_bpermute_b32 v16, v23, v85
	s_waitcnt vmcnt(0) lgkmcnt(0)
	v_mul_f32_e32 v15, v83, v14
	v_bfe_u32 v14, v15, 16, 1
	v_add3_u32 v14, v15, v14, s34
	v_and_b32_e32 v14, 0xffff0000, v14
	v_add_f32_e32 v14, v87, v14
	ds_write_b32 v51, v15
	ds_bpermute_b32 v15, v23, v14
	s_and_saveexec_b64 s[10:11], s[0:1]
	s_cbranch_execz .LBB0_1312
	s_waitcnt lgkmcnt(0)
	v_add_f32_e32 v14, v14, v15
	v_mul_f32_e32 v14, 0x4f800000, v14
	v_add_f32_e32 v85, v85, v16
	v_rndne_f32_e32 v16, v14
	s_mov_b32 s3, 0x2f800000
	v_mul_f32_e64 v14, |v16|, s3
	v_floor_f32_e32 v14, v14
	s_mov_b32 s7, 0xcf800000
	v_fma_f32 v15, v14, s7, |v16|
	v_cvt_u32_f32_e32 v86, v15
	v_cvt_u32_f32_e32 v17, v14
	v_ashrrev_i32_e32 v87, 31, v16
	s_ashr_i32 s9, s8, 31
	v_xor_b32_e32 v16, v86, v87
	s_lshl_b64 s[8:9], s[8:9], 3
	v_xor_b32_e32 v17, v17, v87
	v_sub_co_u32_e32 v16, vcc, v16, v87
	v_lshl_add_u64 v[14:15], v[2:3], 0, s[8:9]
	s_nop 0
	v_subb_co_u32_e32 v17, vcc, v17, v87, vcc
	flat_atomic_add_x2 v[14:15], v[16:17]
	v_mul_f32_e32 v14, 0x4f800000, v85
	v_rndne_f32_e32 v16, v14
	v_mul_f32_e64 v14, |v16|, s3
	v_floor_f32_e32 v14, v14
	v_fma_f32 v15, v14, s7, |v16|
	v_cvt_u32_f32_e32 v85, v15
	v_cvt_u32_f32_e32 v17, v14
	v_ashrrev_i32_e32 v86, 31, v16
	v_lshl_add_u64 v[14:15], v[10:11], 0, s[8:9]
	v_xor_b32_e32 v16, v85, v86
	v_xor_b32_e32 v17, v17, v86
	v_sub_co_u32_e32 v16, vcc, v16, v86
	s_nop 1
	v_subb_co_u32_e32 v17, vcc, v17, v86, vcc
	flat_atomic_add_x2 v[14:15], v[16:17]
